# GEMM epilogue stores write-through (sc1) so the grid barrier's L2 write-back has less dirty data; on top of prep_item prefetch
# baseline (speedup 1.0000x reference)
; #define PG8_STAGE(bufoff, gbase, voff) do { _Pragma("unroll") for (int _i = 0; _i < 2; ++_i) \
;         __builtin_amdgcn_global_load_lds((const unsigned*)((const char*)(gbase) + (voff)[_i]), (LAS unsigned*)(lds + (bufoff) + ldsw + _i * 8192), 16, 0, 0); } while (0)
; #define PG8_LDA(dst, b, h) do { _Pragma("unroll") for (int m = 0; m < 4; ++m) _Pragma("unroll") for (int k = 0; k < 2; ++k) dst[m][k] = *(const LAS bf16x8*)(lds + PG8_SA(b, h) + aoff + m * 2048 + k * 1024); } while (0)
; #define PG8_LDB(dst, b, h) do { _Pragma("unroll") for (int n = 0; n < 2; ++n) _Pragma("unroll") for (int k = 0; k < 2; ++k) dst[n][k] = *(const LAS bf16x8*)(lds + PG8_SB(b, h) + boff + n * 2048 + k * 1024); } while (0)
; #define PG8_MMA(ai, bj, At, Bt) do { __builtin_amdgcn_s_setprio(1); _Pragma("unroll") for (int m = 0; m < 4; ++m) _Pragma("unroll") for (int n = 0; n < 2; ++n) _Pragma("unroll") for (int k = 0; k < 2; ++k) \
;         acc[ai][bj][m][n] = __builtin_amdgcn_mfma_f32_16x16x32_bf16(Bt[n][k], At[m][k], acc[ai][bj][m][n], 0, 0, 0); __builtin_amdgcn_s_setprio(0); } while (0)
; #define PG8_WAIT_L(n) asm volatile("s_waitcnt lgkmcnt(" #n ")" ::: "memory")
; #define PG8_BAR __builtin_amdgcn_s_barrier()
; #define PG8_SCHED __builtin_amdgcn_sched_barrier(0)
; template <class Epi, class Sched>
; __device__ __forceinline__ void gemm_phase(LAS unsigned char* lds, const Gemm g, const Sched& S, const Epi& E) {
;     ...
;             PG8_LDB(B0, 0, 0); PG8_SCHED; PG8_LDA(At, 0, 0); PG8_STAGE(PG8_SA(1, 1), a1 + hstep, voffA);
;             PG8_WAIT_L(8); PG8_BAR; PG8_WAIT_L(0); PG8_MMA(0, 0, At, B0); PG8_BAR; PG8_SCHED;
;             PG8_LDB(B1, 0, 1); PG8_STAGE(PG8_SB(0, 0), b2, voffB);
;             PG8_BAR; PG8_WAIT_L(0); PG8_MMA(0, 1, At, B1); PG8_BAR;
;             PG8_LDA(At, 0, 1); PG8_STAGE(PG8_SA(0, 0), a2, voffA);
;             PG8_BAR; PG8_WAIT_L(0); PG8_MMA(1, 0, At, B0); PG8_BAR; PG8_SCHED;
.LBB0_187:
	s_add_u32 s20, s72, 0xfffc0080
	s_addc_u32 s21, s73, -1
	s_add_i32 s22, 16, 0x10000
	v_add_u32_e32 v153, s22, v154
	ds_read_b128 v[156:159], v153
	ds_read_b128 v[160:163], v153 offset:1024
	ds_read_b128 v[164:167], v153 offset:2048
	ds_read_b128 v[168:171], v153 offset:3072
	s_cmp_eq_u32 s19, 12
	s_cselect_b32 s71, s41, s21
	s_cselect_b32 s70, s78, s20
	s_cselect_b32 s67, s1, s18
	s_cselect_b32 s66, s16, s17
	v_lshl_add_u64 v[216:217], s[72:73], 0, v[148:149]
	s_add_i32 m0, s9, 0xc000
	ds_read_b128 v[172:175], v155
	ds_read_b128 v[188:191], v155 offset:1024
	ds_read_b128 v[192:195], v155 offset:2048
	ds_read_b128 v[196:199], v155 offset:3072
	ds_read_b128 v[200:203], v155 offset:4096
	ds_read_b128 v[204:207], v155 offset:5120
	ds_read_b128 v[208:211], v155 offset:6144
	ds_read_b128 v[212:215], v155 offset:7168
	global_load_lds_dwordx4 v[216:217], off
	v_lshl_add_u64 v[216:217], s[72:73], 0, v[150:151]
	s_add_i32 m0, s9, 0xe000
	s_nop 0
	global_load_lds_dwordx4 v[216:217], off
	s_waitcnt lgkmcnt(8)
	s_barrier
	s_waitcnt lgkmcnt(0)
	s_setprio 1
	s_waitcnt lgkmcnt(0)
	v_mfma_f32_16x16x32_bf16 v[126:129], v[156:159], v[172:175], v[126:129]
	v_mfma_f32_16x16x32_bf16 v[122:125], v[164:167], v[172:175], v[122:125]
	v_mfma_f32_16x16x32_bf16 v[118:121], v[156:159], v[192:195], v[118:121]
	v_mfma_f32_16x16x32_bf16 v[110:113], v[164:167], v[192:195], v[110:113]
	v_mfma_f32_16x16x32_bf16 v[102:105], v[156:159], v[200:203], v[102:105]
	v_mfma_f32_16x16x32_bf16 v[94:97], v[164:167], v[200:203], v[94:97]
	v_mfma_f32_16x16x32_bf16 v[86:89], v[156:159], v[208:211], v[86:89]
	v_mfma_f32_16x16x32_bf16 v[78:81], v[164:167], v[208:211], v[78:81]
	v_mfma_f32_16x16x32_bf16 v[126:129], v[160:163], v[188:191], v[126:129]
	v_mfma_f32_16x16x32_bf16 v[122:125], v[168:171], v[188:191], v[122:125]
	v_mfma_f32_16x16x32_bf16 v[118:121], v[160:163], v[196:199], v[118:121]
	v_mfma_f32_16x16x32_bf16 v[110:113], v[168:171], v[196:199], v[110:113]
	v_mfma_f32_16x16x32_bf16 v[102:105], v[160:163], v[204:207], v[102:105]
	v_mfma_f32_16x16x32_bf16 v[94:97], v[168:171], v[204:207], v[94:97]
	v_mfma_f32_16x16x32_bf16 v[86:89], v[160:163], v[212:215], v[86:89]
	v_mfma_f32_16x16x32_bf16 v[78:81], v[168:171], v[212:215], v[78:81]
	s_setprio 0
	s_barrier
	s_add_i32 s23, 16, 0x14000
	s_add_i32 s20, s22, s8
	v_add_u32_e32 v153, s23, v154
	v_lshl_add_u64 v[232:233], s[66:67], 0, v[144:145]
	s_mov_b32 m0, s20
	ds_read_b128 v[216:219], v153
	ds_read_b128 v[220:223], v153 offset:1024
	ds_read_b128 v[224:227], v153 offset:2048
	ds_read_b128 v[228:231], v153 offset:3072
	global_load_lds_dwordx4 v[232:233], off
	v_lshl_add_u64 v[234:235], s[66:67], 0, v[140:141]
	s_add_i32 m0, s20, 0x2000
	s_nop 0
	global_load_lds_dwordx4 v[234:235], off
	s_barrier
	s_waitcnt lgkmcnt(0)
	s_setprio 1
	s_waitcnt lgkmcnt(0)
	v_mfma_f32_16x16x32_bf16 v[114:117], v[216:219], v[172:175], v[114:117]
	v_mfma_f32_16x16x32_bf16 v[106:109], v[224:227], v[172:175], v[106:109]
	v_mfma_f32_16x16x32_bf16 v[98:101], v[216:219], v[192:195], v[98:101]
	v_mfma_f32_16x16x32_bf16 v[90:93], v[224:227], v[192:195], v[90:93]
	v_mfma_f32_16x16x32_bf16 v[82:85], v[216:219], v[200:203], v[82:85]
	v_mfma_f32_16x16x32_bf16 v[74:77], v[224:227], v[200:203], v[74:77]
	v_mfma_f32_16x16x32_bf16 v[70:73], v[216:219], v[208:211], v[70:73]
	v_mfma_f32_16x16x32_bf16 v[66:69], v[224:227], v[208:211], v[66:69]
	v_mfma_f32_16x16x32_bf16 v[114:117], v[220:223], v[188:191], v[114:117]
	v_mfma_f32_16x16x32_bf16 v[106:109], v[228:231], v[188:191], v[106:109]
	v_mfma_f32_16x16x32_bf16 v[98:101], v[220:223], v[196:199], v[98:101]
	v_mfma_f32_16x16x32_bf16 v[90:93], v[228:231], v[196:199], v[90:93]
	v_mfma_f32_16x16x32_bf16 v[82:85], v[220:223], v[204:207], v[82:85]
	v_mfma_f32_16x16x32_bf16 v[74:77], v[228:231], v[204:207], v[74:77]
	v_mfma_f32_16x16x32_bf16 v[70:73], v[220:223], v[212:215], v[70:73]
	v_mfma_f32_16x16x32_bf16 v[66:69], v[228:231], v[212:215], v[66:69]
	s_setprio 0
	s_mov_b32 m0, s9
	v_lshl_add_u64 v[236:237], s[70:71], 0, v[146:147]
	s_barrier
	ds_read_b128 v[172:175], v155 offset:16384
	ds_read_b128 v[188:191], v155 offset:17408
	ds_read_b128 v[192:195], v155 offset:18432
	ds_read_b128 v[196:199], v155 offset:19456
	ds_read_b128 v[200:203], v155 offset:20480
	ds_read_b128 v[204:207], v155 offset:21504
	ds_read_b128 v[208:211], v155 offset:22528
	ds_read_b128 v[212:215], v155 offset:23552
	global_load_lds_dwordx4 v[236:237], off
	v_lshl_add_u64 v[238:239], s[70:71], 0, v[142:143]
	s_mov_b32 m0, s10
	s_nop 0
	global_load_lds_dwordx4 v[238:239], off
	s_barrier
	s_waitcnt lgkmcnt(0)
	s_setprio 1
	s_waitcnt lgkmcnt(0)
	v_mfma_f32_16x16x32_bf16 v[62:65], v[156:159], v[172:175], v[62:65]
	v_mfma_f32_16x16x32_bf16 v[58:61], v[164:167], v[172:175], v[58:61]
	v_mfma_f32_16x16x32_bf16 v[54:57], v[156:159], v[192:195], v[54:57]
	v_mfma_f32_16x16x32_bf16 v[50:53], v[164:167], v[192:195], v[50:53]
	v_mfma_f32_16x16x32_bf16 v[38:41], v[156:159], v[200:203], v[38:41]
	v_mfma_f32_16x16x32_bf16 v[34:37], v[164:167], v[200:203], v[34:37]
	v_mfma_f32_16x16x32_bf16 v[22:25], v[156:159], v[208:211], v[22:25]
	v_mfma_f32_16x16x32_bf16 v[18:21], v[164:167], v[208:211], v[18:21]
	v_mfma_f32_16x16x32_bf16 v[62:65], v[160:163], v[188:191], v[62:65]
	v_mfma_f32_16x16x32_bf16 v[58:61], v[168:171], v[188:191], v[58:61]
	v_mfma_f32_16x16x32_bf16 v[54:57], v[160:163], v[196:199], v[54:57]
	v_mfma_f32_16x16x32_bf16 v[50:53], v[168:171], v[196:199], v[50:53]
	v_mfma_f32_16x16x32_bf16 v[38:41], v[160:163], v[204:207], v[38:41]
	v_mfma_f32_16x16x32_bf16 v[34:37], v[168:171], v[204:207], v[34:37]
	v_mfma_f32_16x16x32_bf16 v[22:25], v[160:163], v[212:215], v[22:25]
	v_mfma_f32_16x16x32_bf16 v[18:21], v[168:171], v[212:215], v[18:21]
	s_setprio 0
	s_barrier
; #define PG8_STAGE(bufoff, gbase, voff) do { _Pragma("unroll") for (int _i = 0; _i < 2; ++_i) \
;         __builtin_amdgcn_global_load_lds((const unsigned*)((const char*)(gbase) + (voff)[_i]), (LAS unsigned*)(lds + (bufoff) + ldsw + _i * 8192), 16, 0, 0); } while (0)
; #define PG8_LDA(dst, b, h) do { _Pragma("unroll") for (int m = 0; m < 4; ++m) _Pragma("unroll") for (int k = 0; k < 2; ++k) dst[m][k] = *(const LAS bf16x8*)(lds + PG8_SA(b, h) + aoff + m * 2048 + k * 1024); } while (0)
; #define PG8_LDB(dst, b, h) do { _Pragma("unroll") for (int n = 0; n < 2; ++n) _Pragma("unroll") for (int k = 0; k < 2; ++k) dst[n][k] = *(const LAS bf16x8*)(lds + PG8_SB(b, h) + boff + n * 2048 + k * 1024); } while (0)
; #define PG8_MMA(ai, bj, At, Bt) do { __builtin_amdgcn_s_setprio(1); _Pragma("unroll") for (int m = 0; m < 4; ++m) _Pragma("unroll") for (int n = 0; n < 2; ++n) _Pragma("unroll") for (int k = 0; k < 2; ++k) \
;         acc[ai][bj][m][n] = __builtin_amdgcn_mfma_f32_16x16x32_bf16(Bt[n][k], At[m][k], acc[ai][bj][m][n], 0, 0, 0); __builtin_amdgcn_s_setprio(0); } while (0)
; #define PG8_WAIT_V(n) asm volatile("s_waitcnt vmcnt(" #n ")" ::: "memory")
; #define PG8_WAIT_L(n) asm volatile("s_waitcnt lgkmcnt(" #n ")" ::: "memory")
; #define PG8_BAR __builtin_amdgcn_s_barrier()
; #define PG8_SCHED __builtin_amdgcn_sched_barrier(0)
; template <class Epi, class Sched>
; __device__ __forceinline__ void gemm_phase(LAS unsigned char* lds, const Gemm g, const Sched& S, const Epi& E) {
;     ...
;             PG8_STAGE(PG8_SB(0, 1), b2 + hstep, voffB);
;             PG8_WAIT_V(6); PG8_BAR; PG8_MMA(1, 1, At, B1); PG8_BAR;
;             PG8_LDB(B0, 1, 0); PG8_SCHED; PG8_LDA(At, 1, 0); PG8_STAGE(PG8_SA(0, 1), a2 + hstep, voffA);
;             PG8_WAIT_L(8); PG8_BAR; PG8_WAIT_L(0); PG8_MMA(0, 0, At, B0); PG8_BAR; PG8_SCHED;
;             PG8_LDB(B1, 1, 1); PG8_STAGE(PG8_SB(1, 0), b3, voffB);
;             PG8_BAR; PG8_WAIT_L(0); PG8_MMA(0, 1, At, B1); PG8_BAR;
;             PG8_LDA(At, 1, 1); PG8_STAGE(PG8_SA(1, 0), a3, voffA);
	s_add_u32 s20, s66, 0x40000
	s_addc_u32 s21, s67, 0
	s_add_i32 s22, s23, s8
	v_lshl_add_u64 v[156:157], s[20:21], 0, v[144:145]
	s_mov_b32 m0, s22
	s_nop 0
	global_load_lds_dwordx4 v[156:157], off
	v_lshl_add_u64 v[156:157], s[20:21], 0, v[140:141]
	s_add_i32 m0, s22, 0x2000
	s_nop 0
	global_load_lds_dwordx4 v[156:157], off
	s_waitcnt vmcnt(6)
	s_barrier
	s_setprio 1
	v_mfma_f32_16x16x32_bf16 v[46:49], v[216:219], v[172:175], v[46:49]
	v_mfma_f32_16x16x32_bf16 v[42:45], v[224:227], v[172:175], v[42:45]
	v_mfma_f32_16x16x32_bf16 v[30:33], v[216:219], v[192:195], v[30:33]
	v_mfma_f32_16x16x32_bf16 v[26:29], v[224:227], v[192:195], v[26:29]
	v_mfma_f32_16x16x32_bf16 v[14:17], v[216:219], v[200:203], v[14:17]
	v_mfma_f32_16x16x32_bf16 v[10:13], v[224:227], v[200:203], v[10:13]
	v_mfma_f32_16x16x32_bf16 v[4:7], v[216:219], v[208:211], v[4:7]
	v_mfma_f32_16x16x32_bf16 v[0:3], v[224:227], v[208:211], v[0:3]
	v_mfma_f32_16x16x32_bf16 v[46:49], v[220:223], v[188:191], v[46:49]
	v_mfma_f32_16x16x32_bf16 v[42:45], v[228:231], v[188:191], v[42:45]
	v_mfma_f32_16x16x32_bf16 v[30:33], v[220:223], v[196:199], v[30:33]
	v_mfma_f32_16x16x32_bf16 v[26:29], v[228:231], v[196:199], v[26:29]
	v_mfma_f32_16x16x32_bf16 v[14:17], v[220:223], v[204:207], v[14:17]
	v_mfma_f32_16x16x32_bf16 v[10:13], v[228:231], v[204:207], v[10:13]
	v_mfma_f32_16x16x32_bf16 v[4:7], v[220:223], v[212:215], v[4:7]
	v_mfma_f32_16x16x32_bf16 v[0:3], v[228:231], v[212:215], v[0:3]
	s_setprio 0
	s_add_i32 s22, 16, 0x18000
	v_add_u32_e32 v153, s22, v154
	s_barrier
	ds_read_b128 v[156:159], v153
	ds_read_b128 v[160:163], v153 offset:1024
	ds_read_b128 v[164:167], v153 offset:2048
	ds_read_b128 v[168:171], v153 offset:3072
	s_add_u32 s20, s70, 0x40000
	s_addc_u32 s21, s71, 0
	s_mov_b32 m0, s11
	v_lshl_add_u64 v[216:217], s[20:21], 0, v[146:147]
	ds_read_b128 v[172:175], v155 offset:32768
	ds_read_b128 v[188:191], v155 offset:33792
	ds_read_b128 v[192:195], v155 offset:34816
	ds_read_b128 v[196:199], v155 offset:35840
	ds_read_b128 v[200:203], v155 offset:36864
	ds_read_b128 v[204:207], v155 offset:37888
	ds_read_b128 v[208:211], v155 offset:38912
	ds_read_b128 v[212:215], v155 offset:39936
	global_load_lds_dwordx4 v[216:217], off
	v_lshl_add_u64 v[216:217], s[20:21], 0, v[142:143]
	s_mov_b32 m0, s12
	s_nop 0
	global_load_lds_dwordx4 v[216:217], off
	s_waitcnt lgkmcnt(8)
	s_barrier
	s_waitcnt lgkmcnt(0)
	s_setprio 1
	s_waitcnt lgkmcnt(0)
	v_mfma_f32_16x16x32_bf16 v[126:129], v[156:159], v[172:175], v[126:129]
	v_mfma_f32_16x16x32_bf16 v[122:125], v[164:167], v[172:175], v[122:125]
	v_mfma_f32_16x16x32_bf16 v[118:121], v[156:159], v[192:195], v[118:121]
	v_mfma_f32_16x16x32_bf16 v[110:113], v[164:167], v[192:195], v[110:113]
	v_mfma_f32_16x16x32_bf16 v[102:105], v[156:159], v[200:203], v[102:105]
	v_mfma_f32_16x16x32_bf16 v[94:97], v[164:167], v[200:203], v[94:97]
	v_mfma_f32_16x16x32_bf16 v[86:89], v[156:159], v[208:211], v[86:89]
	v_mfma_f32_16x16x32_bf16 v[78:81], v[164:167], v[208:211], v[78:81]
	v_mfma_f32_16x16x32_bf16 v[126:129], v[160:163], v[188:191], v[126:129]
	v_mfma_f32_16x16x32_bf16 v[122:125], v[168:171], v[188:191], v[122:125]
	v_mfma_f32_16x16x32_bf16 v[118:121], v[160:163], v[196:199], v[118:121]
	v_mfma_f32_16x16x32_bf16 v[110:113], v[168:171], v[196:199], v[110:113]
	v_mfma_f32_16x16x32_bf16 v[102:105], v[160:163], v[204:207], v[102:105]
	v_mfma_f32_16x16x32_bf16 v[94:97], v[168:171], v[204:207], v[94:97]
	v_mfma_f32_16x16x32_bf16 v[86:89], v[160:163], v[212:215], v[86:89]
	v_mfma_f32_16x16x32_bf16 v[78:81], v[168:171], v[212:215], v[78:81]
	s_setprio 0
	s_barrier
	s_add_i32 s23, 16, 0x1c000
	s_add_i32 s20, s22, s8
	v_add_u32_e32 v153, s23, v154
	v_lshl_add_u64 v[232:233], v[232:233], 0, s[94:95]
	s_mov_b32 m0, s20
	ds_read_b128 v[216:219], v153
	ds_read_b128 v[220:223], v153 offset:1024
	ds_read_b128 v[224:227], v153 offset:2048
	ds_read_b128 v[228:231], v153 offset:3072
	global_load_lds_dwordx4 v[232:233], off
	v_lshl_add_u64 v[232:233], v[234:235], 0, s[94:95]
	s_add_i32 m0, s20, 0x2000
	s_nop 0
	global_load_lds_dwordx4 v[232:233], off
	s_barrier
	s_waitcnt lgkmcnt(0)
	s_setprio 1
	s_waitcnt lgkmcnt(0)
	v_mfma_f32_16x16x32_bf16 v[114:117], v[216:219], v[172:175], v[114:117]
	v_mfma_f32_16x16x32_bf16 v[106:109], v[224:227], v[172:175], v[106:109]
	v_mfma_f32_16x16x32_bf16 v[98:101], v[216:219], v[192:195], v[98:101]
	v_mfma_f32_16x16x32_bf16 v[90:93], v[224:227], v[192:195], v[90:93]
	v_mfma_f32_16x16x32_bf16 v[82:85], v[216:219], v[200:203], v[82:85]
	v_mfma_f32_16x16x32_bf16 v[74:77], v[224:227], v[200:203], v[74:77]
	v_mfma_f32_16x16x32_bf16 v[70:73], v[216:219], v[208:211], v[70:73]
	v_mfma_f32_16x16x32_bf16 v[66:69], v[224:227], v[208:211], v[66:69]
	v_mfma_f32_16x16x32_bf16 v[114:117], v[220:223], v[188:191], v[114:117]
	v_mfma_f32_16x16x32_bf16 v[106:109], v[228:231], v[188:191], v[106:109]
	v_mfma_f32_16x16x32_bf16 v[98:101], v[220:223], v[196:199], v[98:101]
	v_mfma_f32_16x16x32_bf16 v[90:93], v[228:231], v[196:199], v[90:93]
	v_mfma_f32_16x16x32_bf16 v[82:85], v[220:223], v[204:207], v[82:85]
	v_mfma_f32_16x16x32_bf16 v[74:77], v[228:231], v[204:207], v[74:77]
	v_mfma_f32_16x16x32_bf16 v[70:73], v[220:223], v[212:215], v[70:73]
	v_mfma_f32_16x16x32_bf16 v[66:69], v[228:231], v[212:215], v[66:69]
	s_setprio 0
	s_mov_b32 m0, s13
	v_lshl_add_u64 v[232:233], v[236:237], 0, s[94:95]
	s_barrier
	ds_read_b128 v[172:175], v155 offset:49152
	ds_read_b128 v[188:191], v155 offset:50176
	ds_read_b128 v[192:195], v155 offset:51200
	ds_read_b128 v[196:199], v155 offset:52224
	ds_read_b128 v[200:203], v155 offset:53248
	ds_read_b128 v[204:207], v155 offset:54272
	ds_read_b128 v[208:211], v155 offset:55296
	ds_read_b128 v[212:215], v155 offset:56320
	global_load_lds_dwordx4 v[232:233], off
	v_lshl_add_u64 v[232:233], v[238:239], 0, s[94:95]
	s_mov_b32 m0, s74
	s_nop 0
	global_load_lds_dwordx4 v[232:233], off
	s_barrier
; #define PG8_STAGE(bufoff, gbase, voff) do { _Pragma("unroll") for (int _i = 0; _i < 2; ++_i) \
;         __builtin_amdgcn_global_load_lds((const unsigned*)((const char*)(gbase) + (voff)[_i]), (LAS unsigned*)(lds + (bufoff) + ldsw + _i * 8192), 16, 0, 0); } while (0)
; #define PG8_MMA(ai, bj, At, Bt) do { __builtin_amdgcn_s_setprio(1); _Pragma("unroll") for (int m = 0; m < 4; ++m) _Pragma("unroll") for (int n = 0; n < 2; ++n) _Pragma("unroll") for (int k = 0; k < 2; ++k) \
;         acc[ai][bj][m][n] = __builtin_amdgcn_mfma_f32_16x16x32_bf16(Bt[n][k], At[m][k], acc[ai][bj][m][n], 0, 0, 0); __builtin_amdgcn_s_setprio(0); } while (0)
; #define PG8_WAIT_V(n) asm volatile("s_waitcnt vmcnt(" #n ")" ::: "memory")
; #define PG8_WAIT_L(n) asm volatile("s_waitcnt lgkmcnt(" #n ")" ::: "memory")
; #define PG8_BAR __builtin_amdgcn_s_barrier()
; #define PG8_SCHED __builtin_amdgcn_sched_barrier(0)
; template <class Epi, class Sched>
; __device__ __forceinline__ void gemm_phase(LAS unsigned char* lds, const Gemm g, const Sched& S, const Epi& E) {
;     ...
;             PG8_BAR; PG8_WAIT_L(0); PG8_MMA(1, 0, At, B0); PG8_BAR; PG8_SCHED;
;             PG8_STAGE(PG8_SB(1, 1), b3 + hstep, voffB);
;             PG8_WAIT_V(6); PG8_BAR; PG8_MMA(1, 1, At, B1); PG8_BAR;
;         }
	s_waitcnt lgkmcnt(0)
	s_setprio 1
	s_waitcnt lgkmcnt(0)
	v_mfma_f32_16x16x32_bf16 v[62:65], v[156:159], v[172:175], v[62:65]
	v_mfma_f32_16x16x32_bf16 v[58:61], v[164:167], v[172:175], v[58:61]
	v_mfma_f32_16x16x32_bf16 v[54:57], v[156:159], v[192:195], v[54:57]
	v_mfma_f32_16x16x32_bf16 v[50:53], v[164:167], v[192:195], v[50:53]
	v_mfma_f32_16x16x32_bf16 v[38:41], v[156:159], v[200:203], v[38:41]
	v_mfma_f32_16x16x32_bf16 v[34:37], v[164:167], v[200:203], v[34:37]
	v_mfma_f32_16x16x32_bf16 v[22:25], v[156:159], v[208:211], v[22:25]
	v_mfma_f32_16x16x32_bf16 v[18:21], v[164:167], v[208:211], v[18:21]
	v_mfma_f32_16x16x32_bf16 v[62:65], v[160:163], v[188:191], v[62:65]
	v_mfma_f32_16x16x32_bf16 v[58:61], v[168:171], v[188:191], v[58:61]
	v_mfma_f32_16x16x32_bf16 v[54:57], v[160:163], v[196:199], v[54:57]
	v_mfma_f32_16x16x32_bf16 v[50:53], v[168:171], v[196:199], v[50:53]
	v_mfma_f32_16x16x32_bf16 v[38:41], v[160:163], v[204:207], v[38:41]
	v_mfma_f32_16x16x32_bf16 v[34:37], v[168:171], v[204:207], v[34:37]
	v_mfma_f32_16x16x32_bf16 v[22:25], v[160:163], v[212:215], v[22:25]
	v_mfma_f32_16x16x32_bf16 v[18:21], v[168:171], v[212:215], v[18:21]
	s_setprio 0
	s_barrier
	s_add_u32 s20, s66, 0x40080
	s_addc_u32 s21, s67, 0
	s_add_i32 s22, s23, s8
	v_lshl_add_u64 v[156:157], s[20:21], 0, v[144:145]
	s_mov_b32 m0, s22
	s_nop 0
	global_load_lds_dwordx4 v[156:157], off
	v_lshl_add_u64 v[156:157], s[20:21], 0, v[140:141]
	s_add_i32 m0, s22, 0x2000
	s_nop 0
	global_load_lds_dwordx4 v[156:157], off
	s_waitcnt vmcnt(6)
	s_barrier
	s_setprio 1
	v_mfma_f32_16x16x32_bf16 v[46:49], v[216:219], v[172:175], v[46:49]
	v_mfma_f32_16x16x32_bf16 v[42:45], v[224:227], v[172:175], v[42:45]
	v_mfma_f32_16x16x32_bf16 v[30:33], v[216:219], v[192:195], v[30:33]
	v_mfma_f32_16x16x32_bf16 v[26:29], v[224:227], v[192:195], v[26:29]
	v_mfma_f32_16x16x32_bf16 v[14:17], v[216:219], v[200:203], v[14:17]
	v_mfma_f32_16x16x32_bf16 v[10:13], v[224:227], v[200:203], v[10:13]
	v_mfma_f32_16x16x32_bf16 v[4:7], v[216:219], v[208:211], v[4:7]
	v_mfma_f32_16x16x32_bf16 v[0:3], v[224:227], v[208:211], v[0:3]
	v_mfma_f32_16x16x32_bf16 v[46:49], v[220:223], v[188:191], v[46:49]
	v_mfma_f32_16x16x32_bf16 v[42:45], v[228:231], v[188:191], v[42:45]
	v_mfma_f32_16x16x32_bf16 v[30:33], v[220:223], v[196:199], v[30:33]
	v_mfma_f32_16x16x32_bf16 v[26:29], v[228:231], v[196:199], v[26:29]
	v_mfma_f32_16x16x32_bf16 v[14:17], v[220:223], v[204:207], v[14:17]
	v_mfma_f32_16x16x32_bf16 v[10:13], v[228:231], v[204:207], v[10:13]
	v_mfma_f32_16x16x32_bf16 v[4:7], v[220:223], v[212:215], v[4:7]
	v_mfma_f32_16x16x32_bf16 v[0:3], v[228:231], v[212:215], v[0:3]
	s_setprio 0
	s_add_i32 s19, s19, 2
	s_add_u32 s72, s72, 0x100
	s_addc_u32 s73, s73, 0
	s_add_u32 s17, s17, 0x100
	s_addc_u32 s18, s18, 0
	s_cmp_gt_u32 s19, 13
	s_barrier
	s_cbranch_scc0 .LBB0_187
; __device__ __forceinline__ unsigned pk_bf16(float a, float b) { f32x2 v = {a, b}; bf2_t r = __builtin_convertvector(v, bf2_t); return __builtin_bit_cast(unsigned, r); }
;     __device__ __forceinline__ void operator()(const f32x4 (&acc)[2][2][4][2], const Unit& u, int wr, int wc, int fr, int fq) const {
;         const int row0 = u.pm * BM + wr * 64 + fr; int colt = u.pn * BM; bf16_t* base = O;
;         if (split_cols) { const int t = colt / split_cols; base += (size_t)t * split_stride; colt -= t * split_cols; }
;         const int col0 = colt + wc * 32 + 8 * fq;
; #pragma unroll
;         for (int ai = 0; ai < 2; ++ai)
; #pragma unroll
;             for (int m = 0; m < 4; ++m) { const int row = row0 + ai * HALF + m * 16;
;                 bf16_t* rowp = slot_stride ? base + (size_t)(colt >> 7) * slot_stride + (size_t)row * 128 + wc * 32 + 8 * fq : base + (size_t)row * ldc + col0;
; #pragma unroll
;                 for (int bj = 0; bj < 2; ++bj) { const f32x4 v0 = acc[ai][bj][m][0], v1 = acc[ai][bj][m][1];
;                     u32x4 w; w.x = pk_bf16(v0[0], v0[1]); w.y = pk_bf16(v0[2], v0[3]); w.z = pk_bf16(v1[0], v1[1]); w.w = pk_bf16(v1[2], v1[3]);
;                     *(u32x4*)(rowp + (slot_stride ? (size_t)bj * slot_stride : (size_t)bj * HALF)) = w; } }
	v_lshl_add_u32 v156, s75, 8, v9
	s_lshl_b32 s1, s15, 1
	s_mul_i32 s15, s15, 0x1100000
	s_mul_hi_i32 s1, s1, 0x880000
	s_add_u32 s66, s82, s15
	v_ashrrev_i32_e32 v157, 31, v156
	s_addc_u32 s67, s83, s1
	v_lshlrev_b64 v[158:159], 8, v[156:157]
	v_lshl_add_u64 v[158:159], s[66:67], 0, v[158:159]
	v_lshl_add_u64 v[158:159], v[158:159], 0, s[2:3]
	v_mov_b32_e32 v153, v8
	v_lshl_add_u64 v[158:159], v[158:159], 0, v[152:153]
	v_cvt_pk_bf16_f32 v114, v114, v115
	v_cvt_pk_bf16_f32 v115, v116, v117
	v_cvt_pk_bf16_f32 v116, v106, v107
	v_add_co_u32_e32 v106, vcc, s87, v158
	v_cvt_pk_bf16_f32 v117, v108, v109
	s_nop 0
	v_addc_co_u32_e32 v107, vcc, 0, v159, vcc
	global_store_dwordx4 v[106:107], v[114:117], off sc1
	v_or_b32_e32 v106, 16, v156
	v_ashrrev_i32_e32 v107, 31, v106
	v_lshlrev_b64 v[106:107], 8, v[106:107]
	v_lshl_add_u64 v[106:107], s[66:67], 0, v[106:107]
	v_lshl_add_u64 v[106:107], v[106:107], 0, s[2:3]
	v_lshl_add_u64 v[114:115], v[106:107], 0, v[152:153]
	v_cvt_pk_bf16_f32 v98, v98, v99
	v_cvt_pk_bf16_f32 v99, v100, v101
	v_cvt_pk_bf16_f32 v100, v90, v91
	v_add_co_u32_e32 v90, vcc, s87, v114
	v_cvt_pk_bf16_f32 v101, v92, v93
	s_nop 0
	v_addc_co_u32_e32 v91, vcc, 0, v115, vcc
	global_store_dwordx4 v[90:91], v[98:101], off sc1
	v_or_b32_e32 v90, 32, v156
	v_ashrrev_i32_e32 v91, 31, v90
	v_lshlrev_b64 v[90:91], 8, v[90:91]
	v_lshl_add_u64 v[90:91], s[66:67], 0, v[90:91]
	v_lshl_add_u64 v[90:91], v[90:91], 0, s[2:3]
	v_lshl_add_u64 v[98:99], v[90:91], 0, v[152:153]
	v_cvt_pk_bf16_f32 v82, v82, v83
	v_cvt_pk_bf16_f32 v83, v84, v85
	v_cvt_pk_bf16_f32 v84, v74, v75
	v_add_co_u32_e32 v74, vcc, s87, v98
	v_cvt_pk_bf16_f32 v85, v76, v77
	s_nop 0
	v_addc_co_u32_e32 v75, vcc, 0, v99, vcc
	global_store_dwordx4 v[74:75], v[82:85], off sc1
	v_or_b32_e32 v74, 48, v156
	v_ashrrev_i32_e32 v75, 31, v74
	v_lshlrev_b64 v[74:75], 8, v[74:75]
	v_lshl_add_u64 v[74:75], s[66:67], 0, v[74:75]
	v_lshl_add_u64 v[74:75], v[74:75], 0, s[2:3]
	v_lshl_add_u64 v[82:83], v[74:75], 0, v[152:153]
	v_cvt_pk_bf16_f32 v70, v70, v71
	v_cvt_pk_bf16_f32 v71, v72, v73
	v_cvt_pk_bf16_f32 v72, v66, v67
	v_add_co_u32_e32 v66, vcc, s87, v82
	s_mov_b32 s1, 0x9000
	s_nop 0
	v_addc_co_u32_e32 v67, vcc, 0, v83, vcc
	v_cvt_pk_bf16_f32 v62, v62, v63
	v_cvt_pk_bf16_f32 v63, v64, v65
	v_cvt_pk_bf16_f32 v64, v58, v59
	v_add_co_u32_e32 v58, vcc, s1, v158
	s_mov_b32 s1, 0x889000
	s_nop 0
	v_addc_co_u32_e32 v59, vcc, 0, v159, vcc
	v_cvt_pk_bf16_f32 v65, v60, v61
	v_add_co_u32_e32 v60, vcc, s1, v158
	v_cvt_pk_bf16_f32 v30, v30, v31
	s_nop 0
	v_addc_co_u32_e32 v61, vcc, 0, v159, vcc
	v_cvt_pk_bf16_f32 v31, v32, v33
	v_cvt_pk_bf16_f32 v32, v26, v27
	v_cvt_pk_bf16_f32 v33, v28, v29
	s_mov_b32 s1, 0xb000
	global_store_dwordx4 v[60:61], v[30:33], off sc1
	v_cvt_pk_bf16_f32 v14, v14, v15
	v_cvt_pk_bf16_f32 v15, v16, v17
	v_add_co_u32_e32 v30, vcc, s1, v158
	s_mov_b32 s1, 0x88a000
	s_nop 0
	v_addc_co_u32_e32 v31, vcc, 0, v159, vcc
	v_cvt_pk_bf16_f32 v16, v10, v11
	v_add_co_u32_e32 v10, vcc, s1, v158
	v_cvt_pk_bf16_f32 v4, v4, v5
	s_nop 0
	v_addc_co_u32_e32 v11, vcc, 0, v159, vcc
	v_cvt_pk_bf16_f32 v5, v6, v7
	v_cvt_pk_bf16_f32 v6, v0, v1
	v_add_co_u32_e32 v0, vcc, 0x88b000, v158
	v_cvt_pk_bf16_f32 v17, v12, v13
	s_nop 0
	v_addc_co_u32_e32 v1, vcc, 0, v159, vcc
	v_cvt_pk_bf16_f32 v126, v126, v127
	v_cvt_pk_bf16_f32 v127, v128, v129
	v_cvt_pk_bf16_f32 v128, v122, v123
	v_cvt_pk_bf16_f32 v129, v124, v125
	v_cvt_pk_bf16_f32 v106, v118, v119
	v_cvt_pk_bf16_f32 v107, v120, v121
	v_cvt_pk_bf16_f32 v108, v110, v111
	v_cvt_pk_bf16_f32 v109, v112, v113
	v_cvt_pk_bf16_f32 v90, v102, v103
	v_cvt_pk_bf16_f32 v91, v104, v105
	v_cvt_pk_bf16_f32 v92, v94, v95
	v_cvt_pk_bf16_f32 v93, v96, v97
	v_cvt_pk_bf16_f32 v74, v86, v87
	v_cvt_pk_bf16_f32 v75, v88, v89
	v_cvt_pk_bf16_f32 v76, v78, v79
	v_cvt_pk_bf16_f32 v77, v80, v81
	v_cvt_pk_bf16_f32 v73, v68, v69
	v_cvt_pk_bf16_f32 v46, v46, v47
	v_cvt_pk_bf16_f32 v47, v48, v49
	v_cvt_pk_bf16_f32 v48, v42, v43
	v_cvt_pk_bf16_f32 v49, v44, v45
	v_cvt_pk_bf16_f32 v42, v54, v55
	v_cvt_pk_bf16_f32 v43, v56, v57
	v_cvt_pk_bf16_f32 v44, v50, v51
	v_cvt_pk_bf16_f32 v45, v52, v53
	v_cvt_pk_bf16_f32 v26, v38, v39
	v_cvt_pk_bf16_f32 v27, v40, v41
	v_cvt_pk_bf16_f32 v28, v34, v35
	v_cvt_pk_bf16_f32 v29, v36, v37
	global_store_dwordx4 v[10:11], v[14:17], off sc1
	v_cvt_pk_bf16_f32 v10, v22, v23
	v_cvt_pk_bf16_f32 v11, v24, v25
	v_cvt_pk_bf16_f32 v12, v18, v19
	v_cvt_pk_bf16_f32 v13, v20, v21
	v_cvt_pk_bf16_f32 v7, v2, v3
	s_and_b64 vcc, exec, s[38:39]
	s_mov_b32 s15, s0
	s_mov_b32 s75, s40
	s_mov_b64 s[66:67], s[88:89]
	s_mov_b64 s[70:71], s[42:43]
	global_store_dwordx4 v[158:159], v[126:129], off sc1
	global_store_dwordx4 v[114:115], v[106:109], off sc1
	global_store_dwordx4 v[98:99], v[90:93], off sc1
	global_store_dwordx4 v[82:83], v[74:77], off sc1
	global_store_dwordx4 v[66:67], v[70:73], off sc1
	global_store_dwordx4 v[58:59], v[62:65], off offset:-4096 sc1
	global_store_dwordx4 v[60:61], v[46:49], off offset:-4096 sc1
	global_store_dwordx4 v[58:59], v[42:45], off sc1
	global_store_dwordx4 v[30:31], v[26:29], off offset:-4096 sc1
	global_store_dwordx4 v[30:31], v[10:13], off sc1
	global_store_dwordx4 v[0:1], v[4:7], off sc1
	s_cbranch_vccz .LBB0_184
	s_waitcnt vmcnt(0)
	v_readlane_b32 s14, v244, 49
	v_readlane_b32 s16, v244, 51
	v_readlane_b32 s70, v244, 55
	s_cmpk_gt_u32 s5, 0xff
	v_readlane_b32 s15, v244, 50
	v_readlane_b32 s17, v244, 52
	v_readlane_b32 s71, v244, 56
	s_cbranch_scc1 .LBB0_191
	s_barrier

; #define PG8_STAGE(bufoff, gbase, voff) do { _Pragma("unroll") for (int _i = 0; _i < 2; ++_i) \
;         __builtin_amdgcn_global_load_lds((const unsigned*)((const char*)(gbase) + (voff)[_i]), (LAS unsigned*)(lds + (bufoff) + ldsw + _i * 8192), 16, 0, 0); } while (0)
; #define PG8_LDA(dst, b, h) do { _Pragma("unroll") for (int m = 0; m < 4; ++m) _Pragma("unroll") for (int k = 0; k < 2; ++k) dst[m][k] = *(const LAS bf16x8*)(lds + PG8_SA(b, h) + aoff + m * 2048 + k * 1024); } while (0)
; #define PG8_LDB(dst, b, h) do { _Pragma("unroll") for (int n = 0; n < 2; ++n) _Pragma("unroll") for (int k = 0; k < 2; ++k) dst[n][k] = *(const LAS bf16x8*)(lds + PG8_SB(b, h) + boff + n * 2048 + k * 1024); } while (0)
; #define PG8_MMA(ai, bj, At, Bt) do { __builtin_amdgcn_s_setprio(1); _Pragma("unroll") for (int m = 0; m < 4; ++m) _Pragma("unroll") for (int n = 0; n < 2; ++n) _Pragma("unroll") for (int k = 0; k < 2; ++k) \
;         acc[ai][bj][m][n] = __builtin_amdgcn_mfma_f32_16x16x32_bf16(Bt[n][k], At[m][k], acc[ai][bj][m][n], 0, 0, 0); __builtin_amdgcn_s_setprio(0); } while (0)
; #define PG8_WAIT_L(n) asm volatile("s_waitcnt lgkmcnt(" #n ")" ::: "memory")
; #define PG8_BAR __builtin_amdgcn_s_barrier()
; #define PG8_SCHED __builtin_amdgcn_sched_barrier(0)
; template <class Epi, class Sched>
; __device__ __forceinline__ void gemm_phase(LAS unsigned char* lds, const Gemm g, const Sched& S, const Epi& E) {
;     ...
;             PG8_LDB(B0, 0, 0); PG8_SCHED; PG8_LDA(At, 0, 0); PG8_STAGE(PG8_SA(1, 1), a1 + hstep, voffA);
;             PG8_WAIT_L(8); PG8_BAR; PG8_WAIT_L(0); PG8_MMA(0, 0, At, B0); PG8_BAR; PG8_SCHED;
;             PG8_LDB(B1, 0, 1); PG8_STAGE(PG8_SB(0, 0), b2, voffB);
;             PG8_BAR; PG8_WAIT_L(0); PG8_MMA(0, 1, At, B1); PG8_BAR;
;             PG8_LDA(At, 0, 1); PG8_STAGE(PG8_SA(0, 0), a2, voffA);
;             PG8_BAR; PG8_WAIT_L(0); PG8_MMA(1, 0, At, B0); PG8_BAR; PG8_SCHED;
.LBB0_515:
	s_add_u32 s20, vcc_lo, 0xfffc0080
	s_addc_u32 s21, vcc_hi, -1
	s_add_i32 s22, 16, 0x10000
	v_add_u32_e32 v155, s22, v152
	ds_read_b128 v[156:159], v155
	ds_read_b128 v[160:163], v155 offset:1024
	ds_read_b128 v[164:167], v155 offset:2048
	ds_read_b128 v[168:171], v155 offset:3072
	s_cmp_eq_u32 s19, 12
	s_cselect_b32 s73, s89, s21
	s_cselect_b32 s72, s16, s20
	s_cselect_b32 s67, s17, s18
	s_cselect_b32 s66, s43, s74
	v_lshl_add_u64 v[216:217], vcc, 0, v[148:149]
	s_add_i32 m0, s1, 0xc000
	ds_read_b128 v[172:175], v154
	ds_read_b128 v[188:191], v154 offset:1024
	ds_read_b128 v[192:195], v154 offset:2048
	ds_read_b128 v[196:199], v154 offset:3072
	ds_read_b128 v[200:203], v154 offset:4096
	ds_read_b128 v[204:207], v154 offset:5120
	ds_read_b128 v[208:211], v154 offset:6144
	ds_read_b128 v[212:215], v154 offset:7168
	global_load_lds_dwordx4 v[216:217], off
	v_lshl_add_u64 v[216:217], vcc, 0, v[150:151]
	s_add_i32 m0, s1, 0xe000
	s_nop 0
	global_load_lds_dwordx4 v[216:217], off
	s_waitcnt lgkmcnt(8)
	s_barrier
	s_waitcnt lgkmcnt(0)
	s_setprio 1
	s_waitcnt lgkmcnt(0)
	v_mfma_f32_16x16x32_bf16 v[126:129], v[156:159], v[172:175], v[126:129]
	v_mfma_f32_16x16x32_bf16 v[122:125], v[164:167], v[172:175], v[122:125]
	v_mfma_f32_16x16x32_bf16 v[118:121], v[156:159], v[192:195], v[118:121]
	v_mfma_f32_16x16x32_bf16 v[114:117], v[164:167], v[192:195], v[114:117]
	v_mfma_f32_16x16x32_bf16 v[102:105], v[156:159], v[200:203], v[102:105]
	v_mfma_f32_16x16x32_bf16 v[98:101], v[164:167], v[200:203], v[98:101]
	v_mfma_f32_16x16x32_bf16 v[86:89], v[156:159], v[208:211], v[86:89]
	v_mfma_f32_16x16x32_bf16 v[82:85], v[164:167], v[208:211], v[82:85]
	v_mfma_f32_16x16x32_bf16 v[126:129], v[160:163], v[188:191], v[126:129]
	v_mfma_f32_16x16x32_bf16 v[122:125], v[168:171], v[188:191], v[122:125]
	v_mfma_f32_16x16x32_bf16 v[118:121], v[160:163], v[196:199], v[118:121]
	v_mfma_f32_16x16x32_bf16 v[114:117], v[168:171], v[196:199], v[114:117]
	v_mfma_f32_16x16x32_bf16 v[102:105], v[160:163], v[204:207], v[102:105]
	v_mfma_f32_16x16x32_bf16 v[98:101], v[168:171], v[204:207], v[98:101]
	v_mfma_f32_16x16x32_bf16 v[86:89], v[160:163], v[212:215], v[86:89]
	v_mfma_f32_16x16x32_bf16 v[82:85], v[168:171], v[212:215], v[82:85]
	s_setprio 0
	s_barrier
	s_add_i32 s23, 16, 0x14000
	s_add_i32 s20, s22, s9
	v_add_u32_e32 v155, s23, v152
	v_lshl_add_u64 v[232:233], s[66:67], 0, v[144:145]
	s_mov_b32 m0, s20
	ds_read_b128 v[216:219], v155
	ds_read_b128 v[220:223], v155 offset:1024
	ds_read_b128 v[224:227], v155 offset:2048
	ds_read_b128 v[228:231], v155 offset:3072
	global_load_lds_dwordx4 v[232:233], off
	v_lshl_add_u64 v[234:235], s[66:67], 0, v[140:141]
	s_add_i32 m0, s20, 0x2000
	s_nop 0
	global_load_lds_dwordx4 v[234:235], off
	s_barrier
	s_waitcnt lgkmcnt(0)
	s_setprio 1
	s_waitcnt lgkmcnt(0)
	v_mfma_f32_16x16x32_bf16 v[110:113], v[216:219], v[172:175], v[110:113]
	v_mfma_f32_16x16x32_bf16 v[106:109], v[224:227], v[172:175], v[106:109]
	v_mfma_f32_16x16x32_bf16 v[94:97], v[216:219], v[192:195], v[94:97]
	v_mfma_f32_16x16x32_bf16 v[90:93], v[224:227], v[192:195], v[90:93]
	v_mfma_f32_16x16x32_bf16 v[78:81], v[216:219], v[200:203], v[78:81]
	v_mfma_f32_16x16x32_bf16 v[74:77], v[224:227], v[200:203], v[74:77]
	v_mfma_f32_16x16x32_bf16 v[70:73], v[216:219], v[208:211], v[70:73]
	v_mfma_f32_16x16x32_bf16 v[66:69], v[224:227], v[208:211], v[66:69]
	v_mfma_f32_16x16x32_bf16 v[110:113], v[220:223], v[188:191], v[110:113]
	v_mfma_f32_16x16x32_bf16 v[106:109], v[228:231], v[188:191], v[106:109]
	v_mfma_f32_16x16x32_bf16 v[94:97], v[220:223], v[196:199], v[94:97]
	v_mfma_f32_16x16x32_bf16 v[90:93], v[228:231], v[196:199], v[90:93]
	v_mfma_f32_16x16x32_bf16 v[78:81], v[220:223], v[204:207], v[78:81]
	v_mfma_f32_16x16x32_bf16 v[74:77], v[228:231], v[204:207], v[74:77]
	v_mfma_f32_16x16x32_bf16 v[70:73], v[220:223], v[212:215], v[70:73]
	v_mfma_f32_16x16x32_bf16 v[66:69], v[228:231], v[212:215], v[66:69]
	s_setprio 0
	s_mov_b32 m0, s1
	v_lshl_add_u64 v[236:237], s[72:73], 0, v[146:147]
	s_barrier
	ds_read_b128 v[172:175], v154 offset:16384
	ds_read_b128 v[188:191], v154 offset:17408
	ds_read_b128 v[192:195], v154 offset:18432
	ds_read_b128 v[196:199], v154 offset:19456
	ds_read_b128 v[200:203], v154 offset:20480
	ds_read_b128 v[204:207], v154 offset:21504
	ds_read_b128 v[208:211], v154 offset:22528
	ds_read_b128 v[212:215], v154 offset:23552
	global_load_lds_dwordx4 v[236:237], off
	v_lshl_add_u64 v[238:239], s[72:73], 0, v[142:143]
	s_mov_b32 m0, s11
	s_nop 0
	global_load_lds_dwordx4 v[238:239], off
	s_barrier
	s_waitcnt lgkmcnt(0)
	s_setprio 1
	s_waitcnt lgkmcnt(0)
	v_mfma_f32_16x16x32_bf16 v[62:65], v[156:159], v[172:175], v[62:65]
	v_mfma_f32_16x16x32_bf16 v[58:61], v[164:167], v[172:175], v[58:61]
	v_mfma_f32_16x16x32_bf16 v[54:57], v[156:159], v[192:195], v[54:57]
	v_mfma_f32_16x16x32_bf16 v[50:53], v[164:167], v[192:195], v[50:53]
	v_mfma_f32_16x16x32_bf16 v[38:41], v[156:159], v[200:203], v[38:41]
	v_mfma_f32_16x16x32_bf16 v[34:37], v[164:167], v[200:203], v[34:37]
	v_mfma_f32_16x16x32_bf16 v[22:25], v[156:159], v[208:211], v[22:25]
	v_mfma_f32_16x16x32_bf16 v[18:21], v[164:167], v[208:211], v[18:21]
	v_mfma_f32_16x16x32_bf16 v[62:65], v[160:163], v[188:191], v[62:65]
	v_mfma_f32_16x16x32_bf16 v[58:61], v[168:171], v[188:191], v[58:61]
	v_mfma_f32_16x16x32_bf16 v[54:57], v[160:163], v[196:199], v[54:57]
	v_mfma_f32_16x16x32_bf16 v[50:53], v[168:171], v[196:199], v[50:53]
	v_mfma_f32_16x16x32_bf16 v[38:41], v[160:163], v[204:207], v[38:41]
	v_mfma_f32_16x16x32_bf16 v[34:37], v[168:171], v[204:207], v[34:37]
	v_mfma_f32_16x16x32_bf16 v[22:25], v[160:163], v[212:215], v[22:25]
	v_mfma_f32_16x16x32_bf16 v[18:21], v[168:171], v[212:215], v[18:21]
	s_setprio 0
	s_barrier
; #define PG8_STAGE(bufoff, gbase, voff) do { _Pragma("unroll") for (int _i = 0; _i < 2; ++_i) \
;         __builtin_amdgcn_global_load_lds((const unsigned*)((const char*)(gbase) + (voff)[_i]), (LAS unsigned*)(lds + (bufoff) + ldsw + _i * 8192), 16, 0, 0); } while (0)
; #define PG8_LDA(dst, b, h) do { _Pragma("unroll") for (int m = 0; m < 4; ++m) _Pragma("unroll") for (int k = 0; k < 2; ++k) dst[m][k] = *(const LAS bf16x8*)(lds + PG8_SA(b, h) + aoff + m * 2048 + k * 1024); } while (0)
; #define PG8_LDB(dst, b, h) do { _Pragma("unroll") for (int n = 0; n < 2; ++n) _Pragma("unroll") for (int k = 0; k < 2; ++k) dst[n][k] = *(const LAS bf16x8*)(lds + PG8_SB(b, h) + boff + n * 2048 + k * 1024); } while (0)
; #define PG8_MMA(ai, bj, At, Bt) do { __builtin_amdgcn_s_setprio(1); _Pragma("unroll") for (int m = 0; m < 4; ++m) _Pragma("unroll") for (int n = 0; n < 2; ++n) _Pragma("unroll") for (int k = 0; k < 2; ++k) \
;         acc[ai][bj][m][n] = __builtin_amdgcn_mfma_f32_16x16x32_bf16(Bt[n][k], At[m][k], acc[ai][bj][m][n], 0, 0, 0); __builtin_amdgcn_s_setprio(0); } while (0)
; #define PG8_WAIT_V(n) asm volatile("s_waitcnt vmcnt(" #n ")" ::: "memory")
; #define PG8_WAIT_L(n) asm volatile("s_waitcnt lgkmcnt(" #n ")" ::: "memory")
; #define PG8_BAR __builtin_amdgcn_s_barrier()
; #define PG8_SCHED __builtin_amdgcn_sched_barrier(0)
; template <class Epi, class Sched>
; __device__ __forceinline__ void gemm_phase(LAS unsigned char* lds, const Gemm g, const Sched& S, const Epi& E) {
;     ...
;             PG8_STAGE(PG8_SB(0, 1), b2 + hstep, voffB);
;             PG8_WAIT_V(6); PG8_BAR; PG8_MMA(1, 1, At, B1); PG8_BAR;
;             PG8_LDB(B0, 1, 0); PG8_SCHED; PG8_LDA(At, 1, 0); PG8_STAGE(PG8_SA(0, 1), a2 + hstep, voffA);
;             PG8_WAIT_L(8); PG8_BAR; PG8_WAIT_L(0); PG8_MMA(0, 0, At, B0); PG8_BAR; PG8_SCHED;
;             PG8_LDB(B1, 1, 1); PG8_STAGE(PG8_SB(1, 0), b3, voffB);
;             PG8_BAR; PG8_WAIT_L(0); PG8_MMA(0, 1, At, B1); PG8_BAR;
;             PG8_LDA(At, 1, 1); PG8_STAGE(PG8_SA(1, 0), a3, voffA);
	s_add_u32 s20, s66, 0x40000
	s_addc_u32 s21, s67, 0
	s_add_i32 s22, s23, s9
	v_lshl_add_u64 v[156:157], s[20:21], 0, v[144:145]
	s_mov_b32 m0, s22
	s_nop 0
	global_load_lds_dwordx4 v[156:157], off
	v_lshl_add_u64 v[156:157], s[20:21], 0, v[140:141]
	s_add_i32 m0, s22, 0x2000
	s_nop 0
	global_load_lds_dwordx4 v[156:157], off
	s_waitcnt vmcnt(6)
	s_barrier
	s_setprio 1
	v_mfma_f32_16x16x32_bf16 v[46:49], v[216:219], v[172:175], v[46:49]
	v_mfma_f32_16x16x32_bf16 v[42:45], v[224:227], v[172:175], v[42:45]
	v_mfma_f32_16x16x32_bf16 v[30:33], v[216:219], v[192:195], v[30:33]
	v_mfma_f32_16x16x32_bf16 v[26:29], v[224:227], v[192:195], v[26:29]
	v_mfma_f32_16x16x32_bf16 v[14:17], v[216:219], v[200:203], v[14:17]
	v_mfma_f32_16x16x32_bf16 v[10:13], v[224:227], v[200:203], v[10:13]
	v_mfma_f32_16x16x32_bf16 v[4:7], v[216:219], v[208:211], v[4:7]
	v_mfma_f32_16x16x32_bf16 v[0:3], v[224:227], v[208:211], v[0:3]
	v_mfma_f32_16x16x32_bf16 v[46:49], v[220:223], v[188:191], v[46:49]
	v_mfma_f32_16x16x32_bf16 v[42:45], v[228:231], v[188:191], v[42:45]
	v_mfma_f32_16x16x32_bf16 v[30:33], v[220:223], v[196:199], v[30:33]
	v_mfma_f32_16x16x32_bf16 v[26:29], v[228:231], v[196:199], v[26:29]
	v_mfma_f32_16x16x32_bf16 v[14:17], v[220:223], v[204:207], v[14:17]
	v_mfma_f32_16x16x32_bf16 v[10:13], v[228:231], v[204:207], v[10:13]
	v_mfma_f32_16x16x32_bf16 v[4:7], v[220:223], v[212:215], v[4:7]
	v_mfma_f32_16x16x32_bf16 v[0:3], v[228:231], v[212:215], v[0:3]
	s_setprio 0
	s_add_i32 s22, 16, 0x18000
	v_add_u32_e32 v155, s22, v152
	s_barrier
	ds_read_b128 v[156:159], v155
	ds_read_b128 v[160:163], v155 offset:1024
	ds_read_b128 v[164:167], v155 offset:2048
	ds_read_b128 v[168:171], v155 offset:3072
	s_add_u32 s20, s72, 0x40000
	s_addc_u32 s21, s73, 0
	s_mov_b32 m0, s41
	v_lshl_add_u64 v[216:217], s[20:21], 0, v[146:147]
	ds_read_b128 v[172:175], v154 offset:32768
	ds_read_b128 v[188:191], v154 offset:33792
	ds_read_b128 v[192:195], v154 offset:34816
	ds_read_b128 v[196:199], v154 offset:35840
	ds_read_b128 v[200:203], v154 offset:36864
	ds_read_b128 v[204:207], v154 offset:37888
	ds_read_b128 v[208:211], v154 offset:38912
	ds_read_b128 v[212:215], v154 offset:39936
	global_load_lds_dwordx4 v[216:217], off
	v_lshl_add_u64 v[216:217], s[20:21], 0, v[142:143]
	s_mov_b32 m0, s12
	s_nop 0
	global_load_lds_dwordx4 v[216:217], off
	s_waitcnt lgkmcnt(8)
	s_barrier
	s_waitcnt lgkmcnt(0)
	s_setprio 1
	s_waitcnt lgkmcnt(0)
	v_mfma_f32_16x16x32_bf16 v[126:129], v[156:159], v[172:175], v[126:129]
	v_mfma_f32_16x16x32_bf16 v[122:125], v[164:167], v[172:175], v[122:125]
	v_mfma_f32_16x16x32_bf16 v[118:121], v[156:159], v[192:195], v[118:121]
	v_mfma_f32_16x16x32_bf16 v[114:117], v[164:167], v[192:195], v[114:117]
	v_mfma_f32_16x16x32_bf16 v[102:105], v[156:159], v[200:203], v[102:105]
	v_mfma_f32_16x16x32_bf16 v[98:101], v[164:167], v[200:203], v[98:101]
	v_mfma_f32_16x16x32_bf16 v[86:89], v[156:159], v[208:211], v[86:89]
	v_mfma_f32_16x16x32_bf16 v[82:85], v[164:167], v[208:211], v[82:85]
	v_mfma_f32_16x16x32_bf16 v[126:129], v[160:163], v[188:191], v[126:129]
	v_mfma_f32_16x16x32_bf16 v[122:125], v[168:171], v[188:191], v[122:125]
	v_mfma_f32_16x16x32_bf16 v[118:121], v[160:163], v[196:199], v[118:121]
	v_mfma_f32_16x16x32_bf16 v[114:117], v[168:171], v[196:199], v[114:117]
	v_mfma_f32_16x16x32_bf16 v[102:105], v[160:163], v[204:207], v[102:105]
	v_mfma_f32_16x16x32_bf16 v[98:101], v[168:171], v[204:207], v[98:101]
	v_mfma_f32_16x16x32_bf16 v[86:89], v[160:163], v[212:215], v[86:89]
	v_mfma_f32_16x16x32_bf16 v[82:85], v[168:171], v[212:215], v[82:85]
	s_setprio 0
	s_barrier
	s_add_i32 s23, 16, 0x1c000
	s_add_i32 s20, s22, s9
	v_add_u32_e32 v155, s23, v152
	v_lshl_add_u64 v[232:233], v[232:233], 0, s[94:95]
	s_mov_b32 m0, s20
	ds_read_b128 v[216:219], v155
	ds_read_b128 v[220:223], v155 offset:1024
	ds_read_b128 v[224:227], v155 offset:2048
	ds_read_b128 v[228:231], v155 offset:3072
	global_load_lds_dwordx4 v[232:233], off
	v_lshl_add_u64 v[232:233], v[234:235], 0, s[94:95]
	s_add_i32 m0, s20, 0x2000
	s_nop 0
	global_load_lds_dwordx4 v[232:233], off
	s_barrier
	s_waitcnt lgkmcnt(0)
	s_setprio 1
	s_waitcnt lgkmcnt(0)
	v_mfma_f32_16x16x32_bf16 v[110:113], v[216:219], v[172:175], v[110:113]
	v_mfma_f32_16x16x32_bf16 v[106:109], v[224:227], v[172:175], v[106:109]
	v_mfma_f32_16x16x32_bf16 v[94:97], v[216:219], v[192:195], v[94:97]
	v_mfma_f32_16x16x32_bf16 v[90:93], v[224:227], v[192:195], v[90:93]
	v_mfma_f32_16x16x32_bf16 v[78:81], v[216:219], v[200:203], v[78:81]
	v_mfma_f32_16x16x32_bf16 v[74:77], v[224:227], v[200:203], v[74:77]
	v_mfma_f32_16x16x32_bf16 v[70:73], v[216:219], v[208:211], v[70:73]
	v_mfma_f32_16x16x32_bf16 v[66:69], v[224:227], v[208:211], v[66:69]
	v_mfma_f32_16x16x32_bf16 v[110:113], v[220:223], v[188:191], v[110:113]
	v_mfma_f32_16x16x32_bf16 v[106:109], v[228:231], v[188:191], v[106:109]
	v_mfma_f32_16x16x32_bf16 v[94:97], v[220:223], v[196:199], v[94:97]
	v_mfma_f32_16x16x32_bf16 v[90:93], v[228:231], v[196:199], v[90:93]
	v_mfma_f32_16x16x32_bf16 v[78:81], v[220:223], v[204:207], v[78:81]
	v_mfma_f32_16x16x32_bf16 v[74:77], v[228:231], v[204:207], v[74:77]
	v_mfma_f32_16x16x32_bf16 v[70:73], v[220:223], v[212:215], v[70:73]
	v_mfma_f32_16x16x32_bf16 v[66:69], v[228:231], v[212:215], v[66:69]
	s_setprio 0
	s_mov_b32 m0, s13
	v_lshl_add_u64 v[232:233], v[236:237], 0, s[94:95]
	s_barrier
	ds_read_b128 v[172:175], v154 offset:49152
	ds_read_b128 v[188:191], v154 offset:50176
	ds_read_b128 v[192:195], v154 offset:51200
	ds_read_b128 v[196:199], v154 offset:52224
	ds_read_b128 v[200:203], v154 offset:53248
	ds_read_b128 v[204:207], v154 offset:54272
	ds_read_b128 v[208:211], v154 offset:55296
	ds_read_b128 v[212:215], v154 offset:56320
	global_load_lds_dwordx4 v[232:233], off
	v_lshl_add_u64 v[232:233], v[238:239], 0, s[94:95]
	s_mov_b32 m0, s14
	s_nop 0
	global_load_lds_dwordx4 v[232:233], off
	s_barrier
; #define PG8_STAGE(bufoff, gbase, voff) do { _Pragma("unroll") for (int _i = 0; _i < 2; ++_i) \
;         __builtin_amdgcn_global_load_lds((const unsigned*)((const char*)(gbase) + (voff)[_i]), (LAS unsigned*)(lds + (bufoff) + ldsw + _i * 8192), 16, 0, 0); } while (0)
; #define PG8_MMA(ai, bj, At, Bt) do { __builtin_amdgcn_s_setprio(1); _Pragma("unroll") for (int m = 0; m < 4; ++m) _Pragma("unroll") for (int n = 0; n < 2; ++n) _Pragma("unroll") for (int k = 0; k < 2; ++k) \
;         acc[ai][bj][m][n] = __builtin_amdgcn_mfma_f32_16x16x32_bf16(Bt[n][k], At[m][k], acc[ai][bj][m][n], 0, 0, 0); __builtin_amdgcn_s_setprio(0); } while (0)
; #define PG8_WAIT_V(n) asm volatile("s_waitcnt vmcnt(" #n ")" ::: "memory")
; #define PG8_WAIT_L(n) asm volatile("s_waitcnt lgkmcnt(" #n ")" ::: "memory")
; #define PG8_BAR __builtin_amdgcn_s_barrier()
; #define PG8_SCHED __builtin_amdgcn_sched_barrier(0)
; template <class Epi, class Sched>
; __device__ __forceinline__ void gemm_phase(LAS unsigned char* lds, const Gemm g, const Sched& S, const Epi& E) {
;     ...
;             PG8_BAR; PG8_WAIT_L(0); PG8_MMA(1, 0, At, B0); PG8_BAR; PG8_SCHED;
;             PG8_STAGE(PG8_SB(1, 1), b3 + hstep, voffB);
;             PG8_WAIT_V(6); PG8_BAR; PG8_MMA(1, 1, At, B1); PG8_BAR;
;         }
	s_waitcnt lgkmcnt(0)
	s_setprio 1
	s_waitcnt lgkmcnt(0)
	v_mfma_f32_16x16x32_bf16 v[62:65], v[156:159], v[172:175], v[62:65]
	v_mfma_f32_16x16x32_bf16 v[58:61], v[164:167], v[172:175], v[58:61]
	v_mfma_f32_16x16x32_bf16 v[54:57], v[156:159], v[192:195], v[54:57]
	v_mfma_f32_16x16x32_bf16 v[50:53], v[164:167], v[192:195], v[50:53]
	v_mfma_f32_16x16x32_bf16 v[38:41], v[156:159], v[200:203], v[38:41]
	v_mfma_f32_16x16x32_bf16 v[34:37], v[164:167], v[200:203], v[34:37]
	v_mfma_f32_16x16x32_bf16 v[22:25], v[156:159], v[208:211], v[22:25]
	v_mfma_f32_16x16x32_bf16 v[18:21], v[164:167], v[208:211], v[18:21]
	v_mfma_f32_16x16x32_bf16 v[62:65], v[160:163], v[188:191], v[62:65]
	v_mfma_f32_16x16x32_bf16 v[58:61], v[168:171], v[188:191], v[58:61]
	v_mfma_f32_16x16x32_bf16 v[54:57], v[160:163], v[196:199], v[54:57]
	v_mfma_f32_16x16x32_bf16 v[50:53], v[168:171], v[196:199], v[50:53]
	v_mfma_f32_16x16x32_bf16 v[38:41], v[160:163], v[204:207], v[38:41]
	v_mfma_f32_16x16x32_bf16 v[34:37], v[168:171], v[204:207], v[34:37]
	v_mfma_f32_16x16x32_bf16 v[22:25], v[160:163], v[212:215], v[22:25]
	v_mfma_f32_16x16x32_bf16 v[18:21], v[168:171], v[212:215], v[18:21]
	s_setprio 0
	s_barrier
	s_add_u32 s20, s66, 0x40080
	s_addc_u32 s21, s67, 0
	s_add_i32 s22, s23, s9
	v_lshl_add_u64 v[156:157], s[20:21], 0, v[144:145]
	s_mov_b32 m0, s22
	s_nop 0
	global_load_lds_dwordx4 v[156:157], off
	v_lshl_add_u64 v[156:157], s[20:21], 0, v[140:141]
	s_add_i32 m0, s22, 0x2000
	s_nop 0
	global_load_lds_dwordx4 v[156:157], off
	s_waitcnt vmcnt(6)
	s_barrier
	s_setprio 1
	v_mfma_f32_16x16x32_bf16 v[46:49], v[216:219], v[172:175], v[46:49]
	v_mfma_f32_16x16x32_bf16 v[42:45], v[224:227], v[172:175], v[42:45]
	v_mfma_f32_16x16x32_bf16 v[30:33], v[216:219], v[192:195], v[30:33]
	v_mfma_f32_16x16x32_bf16 v[26:29], v[224:227], v[192:195], v[26:29]
	v_mfma_f32_16x16x32_bf16 v[14:17], v[216:219], v[200:203], v[14:17]
	v_mfma_f32_16x16x32_bf16 v[10:13], v[224:227], v[200:203], v[10:13]
	v_mfma_f32_16x16x32_bf16 v[4:7], v[216:219], v[208:211], v[4:7]
	v_mfma_f32_16x16x32_bf16 v[0:3], v[224:227], v[208:211], v[0:3]
	v_mfma_f32_16x16x32_bf16 v[46:49], v[220:223], v[188:191], v[46:49]
	v_mfma_f32_16x16x32_bf16 v[42:45], v[228:231], v[188:191], v[42:45]
	v_mfma_f32_16x16x32_bf16 v[30:33], v[220:223], v[196:199], v[30:33]
	v_mfma_f32_16x16x32_bf16 v[26:29], v[228:231], v[196:199], v[26:29]
	v_mfma_f32_16x16x32_bf16 v[14:17], v[220:223], v[204:207], v[14:17]
	v_mfma_f32_16x16x32_bf16 v[10:13], v[228:231], v[204:207], v[10:13]
	v_mfma_f32_16x16x32_bf16 v[4:7], v[220:223], v[212:215], v[4:7]
	v_mfma_f32_16x16x32_bf16 v[0:3], v[228:231], v[212:215], v[0:3]
	s_setprio 0
	s_add_i32 s19, s19, 2
	s_add_u32 vcc_lo, vcc_lo, 0x100
	s_addc_u32 vcc_hi, vcc_hi, 0
	s_add_u32 s74, s74, 0x100
	s_addc_u32 s18, s18, 0
	s_cmp_gt_u32 s19, 13
	s_barrier
	s_cbranch_scc0 .LBB0_515
; __device__ __forceinline__ unsigned pk_bf16(float a, float b) { f32x2 v = {a, b}; bf2_t r = __builtin_convertvector(v, bf2_t); return __builtin_bit_cast(unsigned, r); }
;     __device__ __forceinline__ void operator()(const f32x4 (&acc)[2][2][4][2], const Unit& u, int wr, int wc, int fr, int fq) const {
;         const int row0 = u.pm * BM + wr * 64 + fr; int colt = u.pn * BM; bf16_t* base = O;
;         if (split_cols) { const int t = colt / split_cols; base += (size_t)t * split_stride; colt -= t * split_cols; }
;         const int col0 = colt + wc * 32 + 8 * fq;
; #pragma unroll
;         for (int ai = 0; ai < 2; ++ai)
; #pragma unroll
;             for (int m = 0; m < 4; ++m) { const int row = row0 + ai * HALF + m * 16;
;                 bf16_t* rowp = slot_stride ? base + (size_t)(colt >> 7) * slot_stride + (size_t)row * 128 + wc * 32 + 8 * fq : base + (size_t)row * ldc + col0;
; #pragma unroll
;                 for (int bj = 0; bj < 2; ++bj) { const f32x4 v0 = acc[ai][bj][m][0], v1 = acc[ai][bj][m][1];
;                     u32x4 w; w.x = pk_bf16(v0[0], v0[1]); w.y = pk_bf16(v0[2], v0[3]); w.z = pk_bf16(v1[0], v1[1]); w.w = pk_bf16(v1[2], v1[3]);
;                     *(u32x4*)(rowp + (slot_stride ? (size_t)bj * slot_stride : (size_t)bj * HALF)) = w; } }
	v_lshl_add_u32 v156, s40, 8, v9
	v_lshl_or_b32 v158, s0, 8, v153
	v_ashrrev_i32_e32 v159, 31, v158
	v_ashrrev_i32_e32 v157, 31, v156
	v_lshl_add_u64 v[158:159], v[158:159], 1, s[82:83]
	v_lshlrev_b64 v[160:161], 11, v[156:157]
	v_lshl_add_u64 v[160:161], v[158:159], 0, v[160:161]
	s_mov_b32 s0, 0x40000
	s_mov_b64 s[16:17], 0x40000
	v_cvt_pk_bf16_f32 v62, v62, v63
	v_cvt_pk_bf16_f32 v63, v64, v65
	v_cvt_pk_bf16_f32 v64, v58, v59
	v_add_co_u32_e32 v58, vcc, s0, v160
	v_cvt_pk_bf16_f32 v70, v70, v71
	v_cvt_pk_bf16_f32 v71, v72, v73
	v_cvt_pk_bf16_f32 v72, v66, v67
	v_lshl_add_u64 v[66:67], v[160:161], 0, s[16:17]
	v_addc_co_u32_e32 v59, vcc, 0, v161, vcc
	v_cvt_pk_bf16_f32 v46, v46, v47
	v_cvt_pk_bf16_f32 v47, v48, v49
	v_cvt_pk_bf16_f32 v48, v42, v43
	v_cvt_pk_bf16_f32 v49, v44, v45
	s_mov_b32 s0, 0x48000
	global_store_dwordx4 v[66:67], v[46:49], off offset:256 sc1
	s_mov_b64 s[16:17], 0x48000
	v_cvt_pk_bf16_f32 v110, v110, v111
	v_add_co_u32_e32 v48, vcc, s0, v160
	v_cvt_pk_bf16_f32 v111, v112, v113
	v_cvt_pk_bf16_f32 v112, v106, v107
	v_or_b32_e32 v106, 16, v156
	v_lshl_add_u64 v[46:47], v[160:161], 0, s[16:17]
	v_addc_co_u32_e32 v49, vcc, 0, v161, vcc
	v_cvt_pk_bf16_f32 v30, v30, v31
	v_cvt_pk_bf16_f32 v31, v32, v33
	v_cvt_pk_bf16_f32 v32, v26, v27
	v_cvt_pk_bf16_f32 v33, v28, v29
	s_mov_b32 s0, 0x50000
	v_ashrrev_i32_e32 v107, 31, v106
	v_cvt_pk_bf16_f32 v94, v94, v95
	v_cvt_pk_bf16_f32 v95, v96, v97
	v_cvt_pk_bf16_f32 v96, v90, v91
	v_or_b32_e32 v90, 32, v156
	global_store_dwordx4 v[46:47], v[30:33], off offset:256 sc1
	s_mov_b64 s[16:17], 0x50000
	v_cvt_pk_bf16_f32 v113, v108, v109
	v_add_co_u32_e32 v32, vcc, s0, v160
	v_lshlrev_b64 v[106:107], 11, v[106:107]
	v_ashrrev_i32_e32 v91, 31, v90
	v_cvt_pk_bf16_f32 v78, v78, v79
	v_cvt_pk_bf16_f32 v79, v80, v81
	v_cvt_pk_bf16_f32 v80, v74, v75
	v_or_b32_e32 v74, 48, v156
	v_lshl_add_u64 v[30:31], v[160:161], 0, s[16:17]
	v_addc_co_u32_e32 v33, vcc, 0, v161, vcc
	v_cvt_pk_bf16_f32 v14, v14, v15
	v_cvt_pk_bf16_f32 v15, v16, v17
	v_cvt_pk_bf16_f32 v16, v10, v11
	v_cvt_pk_bf16_f32 v17, v12, v13
	s_mov_b32 s0, 0x58000
	global_store_dwordx4 v[160:161], v[110:113], off offset:256 sc1
	v_cvt_pk_bf16_f32 v97, v92, v93
	v_lshlrev_b64 v[90:91], 11, v[90:91]
	v_lshl_add_u64 v[110:111], v[158:159], 0, v[106:107]
	v_ashrrev_i32_e32 v75, 31, v74
	global_store_dwordx4 v[30:31], v[14:17], off offset:256 sc1
	global_store_dwordx4 v[110:111], v[94:97], off offset:256 sc1
	v_cvt_pk_bf16_f32 v81, v76, v77
	v_add_co_u32_e32 v16, vcc, s0, v160
	v_lshl_add_u64 v[94:95], v[158:159], 0, v[90:91]
	v_lshlrev_b64 v[74:75], 11, v[74:75]
	s_mov_b64 s[16:17], 0x58000
	v_addc_co_u32_e32 v17, vcc, 0, v161, vcc
	v_cvt_pk_bf16_f32 v126, v126, v127
	v_cvt_pk_bf16_f32 v127, v128, v129
	v_cvt_pk_bf16_f32 v128, v122, v123
	v_cvt_pk_bf16_f32 v129, v124, v125
	v_cvt_pk_bf16_f32 v106, v118, v119
	v_cvt_pk_bf16_f32 v107, v120, v121
	v_cvt_pk_bf16_f32 v108, v114, v115
	v_cvt_pk_bf16_f32 v109, v116, v117
	v_cvt_pk_bf16_f32 v90, v102, v103
	v_cvt_pk_bf16_f32 v91, v104, v105
	v_cvt_pk_bf16_f32 v92, v98, v99
	v_cvt_pk_bf16_f32 v93, v100, v101
	global_store_dwordx4 v[94:95], v[78:81], off offset:256 sc1
	v_cvt_pk_bf16_f32 v76, v82, v83
	v_cvt_pk_bf16_f32 v77, v84, v85
	v_lshl_add_u64 v[78:79], v[158:159], 0, v[74:75]
	v_cvt_pk_bf16_f32 v74, v86, v87
	v_cvt_pk_bf16_f32 v75, v88, v89
	v_cvt_pk_bf16_f32 v73, v68, v69
	v_cvt_pk_bf16_f32 v65, v60, v61
	v_cvt_pk_bf16_f32 v42, v54, v55
	v_cvt_pk_bf16_f32 v43, v56, v57
	v_cvt_pk_bf16_f32 v44, v50, v51
	v_cvt_pk_bf16_f32 v45, v52, v53
	v_cvt_pk_bf16_f32 v26, v38, v39
	v_cvt_pk_bf16_f32 v27, v40, v41
	v_cvt_pk_bf16_f32 v28, v34, v35
	v_cvt_pk_bf16_f32 v29, v36, v37
	v_lshl_add_u64 v[14:15], v[160:161], 0, s[16:17]
	v_cvt_pk_bf16_f32 v10, v22, v23
	v_cvt_pk_bf16_f32 v11, v24, v25
	v_cvt_pk_bf16_f32 v12, v18, v19
	v_cvt_pk_bf16_f32 v13, v20, v21
	v_cvt_pk_bf16_f32 v4, v4, v5
	v_cvt_pk_bf16_f32 v5, v6, v7
	v_cvt_pk_bf16_f32 v6, v0, v1
	v_cvt_pk_bf16_f32 v7, v2, v3
	s_and_b64 vcc, exec, s[38:39]
	s_mov_b32 s0, s42
	s_mov_b32 s40, s88
	s_mov_b64 s[74:75], s[70:71]
	s_mov_b64 s[72:73], s[78:79]
	global_store_dwordx4 v[160:161], v[126:129], off sc1
	global_store_dwordx4 v[110:111], v[106:109], off sc1
	global_store_dwordx4 v[94:95], v[90:93], off sc1
	global_store_dwordx4 v[78:79], v[74:77], off sc1
	global_store_dwordx4 v[78:79], v[70:73], off offset:256 sc1
	global_store_dwordx4 v[58:59], v[62:65], off sc1
	global_store_dwordx4 v[48:49], v[42:45], off sc1
	global_store_dwordx4 v[32:33], v[26:29], off sc1
	global_store_dwordx4 v[16:17], v[10:13], off sc1
	global_store_dwordx4 v[14:15], v[4:7], off offset:256 sc1
	s_cbranch_vccz .LBB0_512
	s_waitcnt vmcnt(0)
	s_cmpk_gt_u32 s6, 0xff
	s_cbranch_scc1 .LBB0_519
	s_barrier

; #define PG8_STAGE(bufoff, gbase, voff) do { _Pragma("unroll") for (int _i = 0; _i < 2; ++_i) \
;         __builtin_amdgcn_global_load_lds((const unsigned*)((const char*)(gbase) + (voff)[_i]), (LAS unsigned*)(lds + (bufoff) + ldsw + _i * 8192), 16, 0, 0); } while (0)
; #define PG8_LDA(dst, b, h) do { _Pragma("unroll") for (int m = 0; m < 4; ++m) _Pragma("unroll") for (int k = 0; k < 2; ++k) dst[m][k] = *(const LAS bf16x8*)(lds + PG8_SA(b, h) + aoff + m * 2048 + k * 1024); } while (0)
; #define PG8_LDB(dst, b, h) do { _Pragma("unroll") for (int n = 0; n < 2; ++n) _Pragma("unroll") for (int k = 0; k < 2; ++k) dst[n][k] = *(const LAS bf16x8*)(lds + PG8_SB(b, h) + boff + n * 2048 + k * 1024); } while (0)
; #define PG8_MMA(ai, bj, At, Bt) do { __builtin_amdgcn_s_setprio(1); _Pragma("unroll") for (int m = 0; m < 4; ++m) _Pragma("unroll") for (int n = 0; n < 2; ++n) _Pragma("unroll") for (int k = 0; k < 2; ++k) \
;         acc[ai][bj][m][n] = __builtin_amdgcn_mfma_f32_16x16x32_bf16(Bt[n][k], At[m][k], acc[ai][bj][m][n], 0, 0, 0); __builtin_amdgcn_s_setprio(0); } while (0)
; #define PG8_WAIT_L(n) asm volatile("s_waitcnt lgkmcnt(" #n ")" ::: "memory")
; #define PG8_BAR __builtin_amdgcn_s_barrier()
; #define PG8_SCHED __builtin_amdgcn_sched_barrier(0)
; template <class Epi, class Sched>
; __device__ __forceinline__ void gemm_phase(LAS unsigned char* lds, const Gemm g, const Sched& S, const Epi& E) {
;     ...
;             PG8_LDB(B0, 0, 0); PG8_SCHED; PG8_LDA(At, 0, 0); PG8_STAGE(PG8_SA(1, 1), a1 + hstep, voffA);
;             PG8_WAIT_L(8); PG8_BAR; PG8_WAIT_L(0); PG8_MMA(0, 0, At, B0); PG8_BAR; PG8_SCHED;
;             PG8_LDB(B1, 0, 1); PG8_STAGE(PG8_SB(0, 0), b2, voffB);
;             PG8_BAR; PG8_WAIT_L(0); PG8_MMA(0, 1, At, B1); PG8_BAR;
;             PG8_LDA(At, 0, 1); PG8_STAGE(PG8_SA(0, 0), a2, voffA);
;             PG8_BAR; PG8_WAIT_L(0); PG8_MMA(1, 0, At, B0); PG8_BAR; PG8_SCHED;
.LBB0_646:
	s_add_u32 s21, vcc_lo, 0xfffc0080
	s_addc_u32 s22, vcc_hi, -1
	s_add_i32 s23, 16, 0x10000
	v_add_u32_e32 v155, s23, v152
	ds_read_b128 v[156:159], v155
	ds_read_b128 v[160:163], v155 offset:1024
	ds_read_b128 v[164:167], v155 offset:2048
	ds_read_b128 v[168:171], v155 offset:3072
	s_cmp_eq_u32 s20, 12
	s_cselect_b32 s79, s75, s22
	s_cselect_b32 s78, s16, s21
	s_cselect_b32 s71, s17, s19
	s_cselect_b32 s70, s73, s18
	v_lshl_add_u64 v[216:217], vcc, 0, v[148:149]
	s_add_i32 m0, s11, 0xc000
	ds_read_b128 v[172:175], v154
	ds_read_b128 v[188:191], v154 offset:1024
	ds_read_b128 v[192:195], v154 offset:2048
	ds_read_b128 v[196:199], v154 offset:3072
	ds_read_b128 v[200:203], v154 offset:4096
	ds_read_b128 v[204:207], v154 offset:5120
	ds_read_b128 v[208:211], v154 offset:6144
	ds_read_b128 v[212:215], v154 offset:7168
	global_load_lds_dwordx4 v[216:217], off
	v_lshl_add_u64 v[216:217], vcc, 0, v[150:151]
	s_add_i32 m0, s11, 0xe000
	s_nop 0
	global_load_lds_dwordx4 v[216:217], off
	s_waitcnt lgkmcnt(8)
	s_barrier
	s_waitcnt lgkmcnt(0)
	s_setprio 1
	s_waitcnt lgkmcnt(0)
	v_mfma_f32_16x16x32_bf16 v[126:129], v[156:159], v[172:175], v[126:129]
	v_mfma_f32_16x16x32_bf16 v[122:125], v[164:167], v[172:175], v[122:125]
	v_mfma_f32_16x16x32_bf16 v[118:121], v[156:159], v[192:195], v[118:121]
	v_mfma_f32_16x16x32_bf16 v[114:117], v[164:167], v[192:195], v[114:117]
	v_mfma_f32_16x16x32_bf16 v[102:105], v[156:159], v[200:203], v[102:105]
	v_mfma_f32_16x16x32_bf16 v[98:101], v[164:167], v[200:203], v[98:101]
	v_mfma_f32_16x16x32_bf16 v[86:89], v[156:159], v[208:211], v[86:89]
	v_mfma_f32_16x16x32_bf16 v[82:85], v[164:167], v[208:211], v[82:85]
	v_mfma_f32_16x16x32_bf16 v[126:129], v[160:163], v[188:191], v[126:129]
	v_mfma_f32_16x16x32_bf16 v[122:125], v[168:171], v[188:191], v[122:125]
	v_mfma_f32_16x16x32_bf16 v[118:121], v[160:163], v[196:199], v[118:121]
	v_mfma_f32_16x16x32_bf16 v[114:117], v[168:171], v[196:199], v[114:117]
	v_mfma_f32_16x16x32_bf16 v[102:105], v[160:163], v[204:207], v[102:105]
	v_mfma_f32_16x16x32_bf16 v[98:101], v[168:171], v[204:207], v[98:101]
	v_mfma_f32_16x16x32_bf16 v[86:89], v[160:163], v[212:215], v[86:89]
	v_mfma_f32_16x16x32_bf16 v[82:85], v[168:171], v[212:215], v[82:85]
	s_setprio 0
	s_barrier
	s_add_i32 s21, 16, 0x14000
	s_add_i32 s22, s23, s9
	v_add_u32_e32 v155, s21, v152
	v_lshl_add_u64 v[232:233], s[70:71], 0, v[144:145]
	s_mov_b32 m0, s22
	ds_read_b128 v[216:219], v155
	ds_read_b128 v[220:223], v155 offset:1024
	ds_read_b128 v[224:227], v155 offset:2048
	ds_read_b128 v[228:231], v155 offset:3072
	global_load_lds_dwordx4 v[232:233], off
	v_lshl_add_u64 v[234:235], s[70:71], 0, v[140:141]
	s_add_i32 m0, s22, 0x2000
	s_nop 0
	global_load_lds_dwordx4 v[234:235], off
	s_barrier
	s_waitcnt lgkmcnt(0)
	s_setprio 1
	s_waitcnt lgkmcnt(0)
	v_mfma_f32_16x16x32_bf16 v[110:113], v[216:219], v[172:175], v[110:113]
	v_mfma_f32_16x16x32_bf16 v[106:109], v[224:227], v[172:175], v[106:109]
	v_mfma_f32_16x16x32_bf16 v[94:97], v[216:219], v[192:195], v[94:97]
	v_mfma_f32_16x16x32_bf16 v[90:93], v[224:227], v[192:195], v[90:93]
	v_mfma_f32_16x16x32_bf16 v[78:81], v[216:219], v[200:203], v[78:81]
	v_mfma_f32_16x16x32_bf16 v[74:77], v[224:227], v[200:203], v[74:77]
	v_mfma_f32_16x16x32_bf16 v[70:73], v[216:219], v[208:211], v[70:73]
	v_mfma_f32_16x16x32_bf16 v[66:69], v[224:227], v[208:211], v[66:69]
	v_mfma_f32_16x16x32_bf16 v[110:113], v[220:223], v[188:191], v[110:113]
	v_mfma_f32_16x16x32_bf16 v[106:109], v[228:231], v[188:191], v[106:109]
	v_mfma_f32_16x16x32_bf16 v[94:97], v[220:223], v[196:199], v[94:97]
	v_mfma_f32_16x16x32_bf16 v[90:93], v[228:231], v[196:199], v[90:93]
	v_mfma_f32_16x16x32_bf16 v[78:81], v[220:223], v[204:207], v[78:81]
	v_mfma_f32_16x16x32_bf16 v[74:77], v[228:231], v[204:207], v[74:77]
	v_mfma_f32_16x16x32_bf16 v[70:73], v[220:223], v[212:215], v[70:73]
	v_mfma_f32_16x16x32_bf16 v[66:69], v[228:231], v[212:215], v[66:69]
	s_setprio 0
	s_mov_b32 m0, s11
	v_lshl_add_u64 v[236:237], s[78:79], 0, v[146:147]
	s_barrier
	ds_read_b128 v[172:175], v154 offset:16384
	ds_read_b128 v[188:191], v154 offset:17408
	ds_read_b128 v[192:195], v154 offset:18432
	ds_read_b128 v[196:199], v154 offset:19456
	ds_read_b128 v[200:203], v154 offset:20480
	ds_read_b128 v[204:207], v154 offset:21504
	ds_read_b128 v[208:211], v154 offset:22528
	ds_read_b128 v[212:215], v154 offset:23552
	global_load_lds_dwordx4 v[236:237], off
	v_lshl_add_u64 v[238:239], s[78:79], 0, v[142:143]
	s_mov_b32 m0, s41
	s_nop 0
	global_load_lds_dwordx4 v[238:239], off
	s_barrier
	s_waitcnt lgkmcnt(0)
	s_setprio 1
	s_waitcnt lgkmcnt(0)
	v_mfma_f32_16x16x32_bf16 v[62:65], v[156:159], v[172:175], v[62:65]
	v_mfma_f32_16x16x32_bf16 v[58:61], v[164:167], v[172:175], v[58:61]
	v_mfma_f32_16x16x32_bf16 v[54:57], v[156:159], v[192:195], v[54:57]
	v_mfma_f32_16x16x32_bf16 v[50:53], v[164:167], v[192:195], v[50:53]
	v_mfma_f32_16x16x32_bf16 v[38:41], v[156:159], v[200:203], v[38:41]
	v_mfma_f32_16x16x32_bf16 v[34:37], v[164:167], v[200:203], v[34:37]
	v_mfma_f32_16x16x32_bf16 v[22:25], v[156:159], v[208:211], v[22:25]
	v_mfma_f32_16x16x32_bf16 v[18:21], v[164:167], v[208:211], v[18:21]
	v_mfma_f32_16x16x32_bf16 v[62:65], v[160:163], v[188:191], v[62:65]
	v_mfma_f32_16x16x32_bf16 v[58:61], v[168:171], v[188:191], v[58:61]
	v_mfma_f32_16x16x32_bf16 v[54:57], v[160:163], v[196:199], v[54:57]
	v_mfma_f32_16x16x32_bf16 v[50:53], v[168:171], v[196:199], v[50:53]
	v_mfma_f32_16x16x32_bf16 v[38:41], v[160:163], v[204:207], v[38:41]
	v_mfma_f32_16x16x32_bf16 v[34:37], v[168:171], v[204:207], v[34:37]
	v_mfma_f32_16x16x32_bf16 v[22:25], v[160:163], v[212:215], v[22:25]
	v_mfma_f32_16x16x32_bf16 v[18:21], v[168:171], v[212:215], v[18:21]
	s_setprio 0
	s_barrier
; #define PG8_STAGE(bufoff, gbase, voff) do { _Pragma("unroll") for (int _i = 0; _i < 2; ++_i) \
;         __builtin_amdgcn_global_load_lds((const unsigned*)((const char*)(gbase) + (voff)[_i]), (LAS unsigned*)(lds + (bufoff) + ldsw + _i * 8192), 16, 0, 0); } while (0)
; #define PG8_LDA(dst, b, h) do { _Pragma("unroll") for (int m = 0; m < 4; ++m) _Pragma("unroll") for (int k = 0; k < 2; ++k) dst[m][k] = *(const LAS bf16x8*)(lds + PG8_SA(b, h) + aoff + m * 2048 + k * 1024); } while (0)
; #define PG8_LDB(dst, b, h) do { _Pragma("unroll") for (int n = 0; n < 2; ++n) _Pragma("unroll") for (int k = 0; k < 2; ++k) dst[n][k] = *(const LAS bf16x8*)(lds + PG8_SB(b, h) + boff + n * 2048 + k * 1024); } while (0)
; #define PG8_MMA(ai, bj, At, Bt) do { __builtin_amdgcn_s_setprio(1); _Pragma("unroll") for (int m = 0; m < 4; ++m) _Pragma("unroll") for (int n = 0; n < 2; ++n) _Pragma("unroll") for (int k = 0; k < 2; ++k) \
;         acc[ai][bj][m][n] = __builtin_amdgcn_mfma_f32_16x16x32_bf16(Bt[n][k], At[m][k], acc[ai][bj][m][n], 0, 0, 0); __builtin_amdgcn_s_setprio(0); } while (0)
; #define PG8_WAIT_V(n) asm volatile("s_waitcnt vmcnt(" #n ")" ::: "memory")
; #define PG8_WAIT_L(n) asm volatile("s_waitcnt lgkmcnt(" #n ")" ::: "memory")
; #define PG8_BAR __builtin_amdgcn_s_barrier()
; #define PG8_SCHED __builtin_amdgcn_sched_barrier(0)
; template <class Epi, class Sched>
; __device__ __forceinline__ void gemm_phase(LAS unsigned char* lds, const Gemm g, const Sched& S, const Epi& E) {
;     ...
;             PG8_STAGE(PG8_SB(0, 1), b2 + hstep, voffB);
;             PG8_WAIT_V(6); PG8_BAR; PG8_MMA(1, 1, At, B1); PG8_BAR;
;             PG8_LDB(B0, 1, 0); PG8_SCHED; PG8_LDA(At, 1, 0); PG8_STAGE(PG8_SA(0, 1), a2 + hstep, voffA);
;             PG8_WAIT_L(8); PG8_BAR; PG8_WAIT_L(0); PG8_MMA(0, 0, At, B0); PG8_BAR; PG8_SCHED;
;             PG8_LDB(B1, 1, 1); PG8_STAGE(PG8_SB(1, 0), b3, voffB);
;             PG8_BAR; PG8_WAIT_L(0); PG8_MMA(0, 1, At, B1); PG8_BAR;
;             PG8_LDA(At, 1, 1); PG8_STAGE(PG8_SA(1, 0), a3, voffA);
	s_add_u32 s22, s70, 0x40000
	s_addc_u32 s23, s71, 0
	s_add_i32 s21, s21, s9
	v_lshl_add_u64 v[156:157], s[22:23], 0, v[144:145]
	s_mov_b32 m0, s21
	s_nop 0
	global_load_lds_dwordx4 v[156:157], off
	v_lshl_add_u64 v[156:157], s[22:23], 0, v[140:141]
	s_add_i32 m0, s21, 0x2000
	s_nop 0
	global_load_lds_dwordx4 v[156:157], off
	s_waitcnt vmcnt(6)
	s_barrier
	s_setprio 1
	v_mfma_f32_16x16x32_bf16 v[46:49], v[216:219], v[172:175], v[46:49]
	v_mfma_f32_16x16x32_bf16 v[42:45], v[224:227], v[172:175], v[42:45]
	v_mfma_f32_16x16x32_bf16 v[30:33], v[216:219], v[192:195], v[30:33]
	v_mfma_f32_16x16x32_bf16 v[26:29], v[224:227], v[192:195], v[26:29]
	v_mfma_f32_16x16x32_bf16 v[14:17], v[216:219], v[200:203], v[14:17]
	v_mfma_f32_16x16x32_bf16 v[10:13], v[224:227], v[200:203], v[10:13]
	v_mfma_f32_16x16x32_bf16 v[4:7], v[216:219], v[208:211], v[4:7]
	v_mfma_f32_16x16x32_bf16 v[0:3], v[224:227], v[208:211], v[0:3]
	v_mfma_f32_16x16x32_bf16 v[46:49], v[220:223], v[188:191], v[46:49]
	v_mfma_f32_16x16x32_bf16 v[42:45], v[228:231], v[188:191], v[42:45]
	v_mfma_f32_16x16x32_bf16 v[30:33], v[220:223], v[196:199], v[30:33]
	v_mfma_f32_16x16x32_bf16 v[26:29], v[228:231], v[196:199], v[26:29]
	v_mfma_f32_16x16x32_bf16 v[14:17], v[220:223], v[204:207], v[14:17]
	v_mfma_f32_16x16x32_bf16 v[10:13], v[228:231], v[204:207], v[10:13]
	v_mfma_f32_16x16x32_bf16 v[4:7], v[220:223], v[212:215], v[4:7]
	v_mfma_f32_16x16x32_bf16 v[0:3], v[228:231], v[212:215], v[0:3]
	s_setprio 0
	s_add_i32 s21, 16, 0x18000
	v_add_u32_e32 v155, s21, v152
	s_barrier
	ds_read_b128 v[156:159], v155
	ds_read_b128 v[160:163], v155 offset:1024
	ds_read_b128 v[164:167], v155 offset:2048
	ds_read_b128 v[168:171], v155 offset:3072
	s_add_u32 s22, s78, 0x40000
	s_addc_u32 s23, s79, 0
	s_mov_b32 m0, s12
	v_lshl_add_u64 v[216:217], s[22:23], 0, v[146:147]
	ds_read_b128 v[172:175], v154 offset:32768
	ds_read_b128 v[188:191], v154 offset:33792
	ds_read_b128 v[192:195], v154 offset:34816
	ds_read_b128 v[196:199], v154 offset:35840
	ds_read_b128 v[200:203], v154 offset:36864
	ds_read_b128 v[204:207], v154 offset:37888
	ds_read_b128 v[208:211], v154 offset:38912
	ds_read_b128 v[212:215], v154 offset:39936
	global_load_lds_dwordx4 v[216:217], off
	v_lshl_add_u64 v[216:217], s[22:23], 0, v[142:143]
	s_mov_b32 m0, s13
	s_nop 0
	global_load_lds_dwordx4 v[216:217], off
	s_waitcnt lgkmcnt(8)
	s_barrier
	s_waitcnt lgkmcnt(0)
	s_setprio 1
	s_waitcnt lgkmcnt(0)
	v_mfma_f32_16x16x32_bf16 v[126:129], v[156:159], v[172:175], v[126:129]
	v_mfma_f32_16x16x32_bf16 v[122:125], v[164:167], v[172:175], v[122:125]
	v_mfma_f32_16x16x32_bf16 v[118:121], v[156:159], v[192:195], v[118:121]
	v_mfma_f32_16x16x32_bf16 v[114:117], v[164:167], v[192:195], v[114:117]
	v_mfma_f32_16x16x32_bf16 v[102:105], v[156:159], v[200:203], v[102:105]
	v_mfma_f32_16x16x32_bf16 v[98:101], v[164:167], v[200:203], v[98:101]
	v_mfma_f32_16x16x32_bf16 v[86:89], v[156:159], v[208:211], v[86:89]
	v_mfma_f32_16x16x32_bf16 v[82:85], v[164:167], v[208:211], v[82:85]
	v_mfma_f32_16x16x32_bf16 v[126:129], v[160:163], v[188:191], v[126:129]
	v_mfma_f32_16x16x32_bf16 v[122:125], v[168:171], v[188:191], v[122:125]
	v_mfma_f32_16x16x32_bf16 v[118:121], v[160:163], v[196:199], v[118:121]
	v_mfma_f32_16x16x32_bf16 v[114:117], v[168:171], v[196:199], v[114:117]
	v_mfma_f32_16x16x32_bf16 v[102:105], v[160:163], v[204:207], v[102:105]
	v_mfma_f32_16x16x32_bf16 v[98:101], v[168:171], v[204:207], v[98:101]
	v_mfma_f32_16x16x32_bf16 v[86:89], v[160:163], v[212:215], v[86:89]
	v_mfma_f32_16x16x32_bf16 v[82:85], v[168:171], v[212:215], v[82:85]
	s_setprio 0
	s_barrier
	s_add_i32 s78, 16, 0x1c000
	s_add_i32 s21, s21, s9
	v_add_u32_e32 v155, s78, v152
	v_lshl_add_u64 v[232:233], v[232:233], 0, s[94:95]
	s_mov_b32 m0, s21
	ds_read_b128 v[216:219], v155
	ds_read_b128 v[220:223], v155 offset:1024
	ds_read_b128 v[224:227], v155 offset:2048
	ds_read_b128 v[228:231], v155 offset:3072
	global_load_lds_dwordx4 v[232:233], off
	v_lshl_add_u64 v[232:233], v[234:235], 0, s[94:95]
	s_add_i32 m0, s21, 0x2000
	s_nop 0
	global_load_lds_dwordx4 v[232:233], off
	s_barrier
	s_waitcnt lgkmcnt(0)
	s_setprio 1
	s_waitcnt lgkmcnt(0)
	v_mfma_f32_16x16x32_bf16 v[110:113], v[216:219], v[172:175], v[110:113]
	v_mfma_f32_16x16x32_bf16 v[106:109], v[224:227], v[172:175], v[106:109]
	v_mfma_f32_16x16x32_bf16 v[94:97], v[216:219], v[192:195], v[94:97]
	v_mfma_f32_16x16x32_bf16 v[90:93], v[224:227], v[192:195], v[90:93]
	v_mfma_f32_16x16x32_bf16 v[78:81], v[216:219], v[200:203], v[78:81]
	v_mfma_f32_16x16x32_bf16 v[74:77], v[224:227], v[200:203], v[74:77]
	v_mfma_f32_16x16x32_bf16 v[70:73], v[216:219], v[208:211], v[70:73]
	v_mfma_f32_16x16x32_bf16 v[66:69], v[224:227], v[208:211], v[66:69]
	v_mfma_f32_16x16x32_bf16 v[110:113], v[220:223], v[188:191], v[110:113]
	v_mfma_f32_16x16x32_bf16 v[106:109], v[228:231], v[188:191], v[106:109]
	v_mfma_f32_16x16x32_bf16 v[94:97], v[220:223], v[196:199], v[94:97]
	v_mfma_f32_16x16x32_bf16 v[90:93], v[228:231], v[196:199], v[90:93]
	v_mfma_f32_16x16x32_bf16 v[78:81], v[220:223], v[204:207], v[78:81]
	v_mfma_f32_16x16x32_bf16 v[74:77], v[228:231], v[204:207], v[74:77]
	v_mfma_f32_16x16x32_bf16 v[70:73], v[220:223], v[212:215], v[70:73]
	v_mfma_f32_16x16x32_bf16 v[66:69], v[228:231], v[212:215], v[66:69]
	s_setprio 0
	s_mov_b32 m0, s14
	v_lshl_add_u64 v[232:233], v[236:237], 0, s[94:95]
	s_barrier
	ds_read_b128 v[172:175], v154 offset:49152
	ds_read_b128 v[188:191], v154 offset:50176
	ds_read_b128 v[192:195], v154 offset:51200
	ds_read_b128 v[196:199], v154 offset:52224
	ds_read_b128 v[200:203], v154 offset:53248
	ds_read_b128 v[204:207], v154 offset:54272
	ds_read_b128 v[208:211], v154 offset:55296
	ds_read_b128 v[212:215], v154 offset:56320
	global_load_lds_dwordx4 v[232:233], off
	v_lshl_add_u64 v[232:233], v[238:239], 0, s[94:95]
	s_mov_b32 m0, s15
	s_nop 0
	global_load_lds_dwordx4 v[232:233], off
	s_barrier
; #define PG8_STAGE(bufoff, gbase, voff) do { _Pragma("unroll") for (int _i = 0; _i < 2; ++_i) \
;         __builtin_amdgcn_global_load_lds((const unsigned*)((const char*)(gbase) + (voff)[_i]), (LAS unsigned*)(lds + (bufoff) + ldsw + _i * 8192), 16, 0, 0); } while (0)
; #define PG8_MMA(ai, bj, At, Bt) do { __builtin_amdgcn_s_setprio(1); _Pragma("unroll") for (int m = 0; m < 4; ++m) _Pragma("unroll") for (int n = 0; n < 2; ++n) _Pragma("unroll") for (int k = 0; k < 2; ++k) \
;         acc[ai][bj][m][n] = __builtin_amdgcn_mfma_f32_16x16x32_bf16(Bt[n][k], At[m][k], acc[ai][bj][m][n], 0, 0, 0); __builtin_amdgcn_s_setprio(0); } while (0)
; #define PG8_WAIT_V(n) asm volatile("s_waitcnt vmcnt(" #n ")" ::: "memory")
; #define PG8_WAIT_L(n) asm volatile("s_waitcnt lgkmcnt(" #n ")" ::: "memory")
; #define PG8_BAR __builtin_amdgcn_s_barrier()
; #define PG8_SCHED __builtin_amdgcn_sched_barrier(0)
; template <class Epi, class Sched>
; __device__ __forceinline__ void gemm_phase(LAS unsigned char* lds, const Gemm g, const Sched& S, const Epi& E) {
;     ...
;             PG8_BAR; PG8_WAIT_L(0); PG8_MMA(1, 0, At, B0); PG8_BAR; PG8_SCHED;
;             PG8_STAGE(PG8_SB(1, 1), b3 + hstep, voffB);
;             PG8_WAIT_V(6); PG8_BAR; PG8_MMA(1, 1, At, B1); PG8_BAR;
;         }
	s_waitcnt lgkmcnt(0)
	s_setprio 1
	s_waitcnt lgkmcnt(0)
	v_mfma_f32_16x16x32_bf16 v[62:65], v[156:159], v[172:175], v[62:65]
	v_mfma_f32_16x16x32_bf16 v[58:61], v[164:167], v[172:175], v[58:61]
	v_mfma_f32_16x16x32_bf16 v[54:57], v[156:159], v[192:195], v[54:57]
	v_mfma_f32_16x16x32_bf16 v[50:53], v[164:167], v[192:195], v[50:53]
	v_mfma_f32_16x16x32_bf16 v[38:41], v[156:159], v[200:203], v[38:41]
	v_mfma_f32_16x16x32_bf16 v[34:37], v[164:167], v[200:203], v[34:37]
	v_mfma_f32_16x16x32_bf16 v[22:25], v[156:159], v[208:211], v[22:25]
	v_mfma_f32_16x16x32_bf16 v[18:21], v[164:167], v[208:211], v[18:21]
	v_mfma_f32_16x16x32_bf16 v[62:65], v[160:163], v[188:191], v[62:65]
	v_mfma_f32_16x16x32_bf16 v[58:61], v[168:171], v[188:191], v[58:61]
	v_mfma_f32_16x16x32_bf16 v[54:57], v[160:163], v[196:199], v[54:57]
	v_mfma_f32_16x16x32_bf16 v[50:53], v[168:171], v[196:199], v[50:53]
	v_mfma_f32_16x16x32_bf16 v[38:41], v[160:163], v[204:207], v[38:41]
	v_mfma_f32_16x16x32_bf16 v[34:37], v[168:171], v[204:207], v[34:37]
	v_mfma_f32_16x16x32_bf16 v[22:25], v[160:163], v[212:215], v[22:25]
	v_mfma_f32_16x16x32_bf16 v[18:21], v[168:171], v[212:215], v[18:21]
	s_setprio 0
	s_barrier
	s_add_u32 s22, s70, 0x40080
	s_addc_u32 s23, s71, 0
	s_add_i32 s21, s78, s9
	v_lshl_add_u64 v[156:157], s[22:23], 0, v[144:145]
	s_mov_b32 m0, s21
	s_nop 0
	global_load_lds_dwordx4 v[156:157], off
	v_lshl_add_u64 v[156:157], s[22:23], 0, v[140:141]
	s_add_i32 m0, s21, 0x2000
	s_nop 0
	global_load_lds_dwordx4 v[156:157], off
	s_waitcnt vmcnt(6)
	s_barrier
	s_setprio 1
	v_mfma_f32_16x16x32_bf16 v[46:49], v[216:219], v[172:175], v[46:49]
	v_mfma_f32_16x16x32_bf16 v[42:45], v[224:227], v[172:175], v[42:45]
	v_mfma_f32_16x16x32_bf16 v[30:33], v[216:219], v[192:195], v[30:33]
	v_mfma_f32_16x16x32_bf16 v[26:29], v[224:227], v[192:195], v[26:29]
	v_mfma_f32_16x16x32_bf16 v[14:17], v[216:219], v[200:203], v[14:17]
	v_mfma_f32_16x16x32_bf16 v[10:13], v[224:227], v[200:203], v[10:13]
	v_mfma_f32_16x16x32_bf16 v[4:7], v[216:219], v[208:211], v[4:7]
	v_mfma_f32_16x16x32_bf16 v[0:3], v[224:227], v[208:211], v[0:3]
	v_mfma_f32_16x16x32_bf16 v[46:49], v[220:223], v[188:191], v[46:49]
	v_mfma_f32_16x16x32_bf16 v[42:45], v[228:231], v[188:191], v[42:45]
	v_mfma_f32_16x16x32_bf16 v[30:33], v[220:223], v[196:199], v[30:33]
	v_mfma_f32_16x16x32_bf16 v[26:29], v[228:231], v[196:199], v[26:29]
	v_mfma_f32_16x16x32_bf16 v[14:17], v[220:223], v[204:207], v[14:17]
	v_mfma_f32_16x16x32_bf16 v[10:13], v[228:231], v[204:207], v[10:13]
	v_mfma_f32_16x16x32_bf16 v[4:7], v[220:223], v[212:215], v[4:7]
	v_mfma_f32_16x16x32_bf16 v[0:3], v[228:231], v[212:215], v[0:3]
	s_setprio 0
	s_add_i32 s20, s20, 2
	s_add_u32 vcc_lo, vcc_lo, 0x100
	s_addc_u32 vcc_hi, vcc_hi, 0
	s_add_u32 s18, s18, 0x100
	s_addc_u32 s19, s19, 0
	s_cmp_gt_u32 s20, 13
	s_barrier
	s_cbranch_scc0 .LBB0_646
; __device__ __forceinline__ unsigned pk_bf16(float a, float b) { f32x2 v = {a, b}; bf2_t r = __builtin_convertvector(v, bf2_t); return __builtin_bit_cast(unsigned, r); }
; #define PG8_WAIT_V(n) asm volatile("s_waitcnt vmcnt(" #n ")" ::: "memory")
; #define PG8_BAR __builtin_amdgcn_s_barrier()
;     __device__ __forceinline__ void operator()(const f32x4 (&acc)[2][2][4][2], const Unit& u, int wr, int wc, int fr, int fq) const {
;         const int row0 = u.pm * BM + wr * 64 + fr; int colt = u.pn * BM; bf16_t* base = O;
;         if (split_cols) { const int t = colt / split_cols; base += (size_t)t * split_stride; colt -= t * split_cols; }
;         const int col0 = colt + wc * 32 + 8 * fq;
; #pragma unroll
;         for (int ai = 0; ai < 2; ++ai)
; #pragma unroll
;             for (int m = 0; m < 4; ++m) { const int row = row0 + ai * HALF + m * 16;
;                 bf16_t* rowp = slot_stride ? base + (size_t)(colt >> 7) * slot_stride + (size_t)row * 128 + wc * 32 + 8 * fq : base + (size_t)row * ldc + col0;
; #pragma unroll
;                 for (int bj = 0; bj < 2; ++bj) { const f32x4 v0 = acc[ai][bj][m][0], v1 = acc[ai][bj][m][1];
;                     u32x4 w; w.x = pk_bf16(v0[0], v0[1]); w.y = pk_bf16(v0[2], v0[3]); w.z = pk_bf16(v1[0], v1[1]); w.w = pk_bf16(v1[2], v1[3]);
;                     *(u32x4*)(rowp + (slot_stride ? (size_t)bj * slot_stride : (size_t)bj * HALF)) = w; } }
; template <class Epi, class Sched>
; __device__ __forceinline__ void gemm_phase(LAS unsigned char* lds, const Gemm g, const Sched& S, const Epi& E) {
;     ...
;         E(acc, cur, wr, wc, fr, fq); S.done(cur);
;         if (!has_next) break;
; #pragma unroll
;         for (int a = 0; a < 2; ++a)
; #pragma unroll
;             for (int b = 0; b < 2; ++b)
; #pragma unroll
;                 for (int m = 0; m < 4; ++m)
; #pragma unroll
;                     for (int n = 0; n < 2; ++n) acc[a][b][m][n] = (f32x4){0.f, 0.f, 0.f, 0.f};
;         cur = nxt; cA = nA; cB = nB; ++ui;
;     }
;     PG8_WAIT_V(0);
;     if (wr == 0) PG8_BAR;
;     PG8_BAR;
	s_mul_hi_i32 s16, s40, 0x2e8ba2e9
	s_lshr_b32 s17, s16, 31
	s_ashr_i32 s16, s16, 1
	s_add_i32 s19, s16, s17
	s_lshl_b32 s18, s40, 8
	s_mul_i32 s16, s19, 0xbb00000
	s_mul_hi_i32 s17, s19, 0xbb00000
	s_add_u32 s16, s82, s16
	s_mulk_i32 s19, 0xf500
	s_addc_u32 s17, s83, s17
	s_add_i32 s19, s19, s18
	v_or_b32_e32 v156, s19, v153
	v_lshl_add_u32 v155, s42, 8, v9
	v_ashrrev_i32_e32 v157, 31, v156
	v_lshl_add_u64 v[156:157], v[156:157], 1, s[16:17]
	v_cvt_pk_bf16_f32 v70, v70, v71
	v_cvt_pk_bf16_f32 v71, v72, v73
	v_cvt_pk_bf16_f32 v72, v66, v67
	v_add_u32_e32 v66, 0x80, v155
	v_mad_i64_i32 v[158:159], s[16:17], v155, s81, v[156:157]
	v_cvt_pk_bf16_f32 v110, v110, v111
	v_cvt_pk_bf16_f32 v111, v112, v113
	v_cvt_pk_bf16_f32 v112, v106, v107
	v_cvt_pk_bf16_f32 v113, v108, v109
	v_or_b32_e32 v106, 16, v155
	v_mad_i64_i32 v[66:67], s[16:17], v66, s81, v[156:157]
	v_cvt_pk_bf16_f32 v46, v46, v47
	v_cvt_pk_bf16_f32 v47, v48, v49
	v_cvt_pk_bf16_f32 v48, v42, v43
	v_cvt_pk_bf16_f32 v49, v44, v45
	v_add_u32_e32 v42, 0x90, v155
	global_store_dwordx4 v[158:159], v[110:113], off offset:256 sc1
	v_cvt_pk_bf16_f32 v94, v94, v95
	v_cvt_pk_bf16_f32 v95, v96, v97
	v_mad_i64_i32 v[110:111], s[16:17], v106, s81, v[156:157]
	v_cvt_pk_bf16_f32 v96, v90, v91
	v_cvt_pk_bf16_f32 v97, v92, v93
	v_or_b32_e32 v90, 32, v155
	global_store_dwordx4 v[66:67], v[46:49], off offset:256 sc1
	v_cvt_pk_bf16_f32 v30, v30, v31
	v_cvt_pk_bf16_f32 v31, v32, v33
	v_mad_i64_i32 v[46:47], s[16:17], v42, s81, v[156:157]
	v_cvt_pk_bf16_f32 v32, v26, v27
	v_cvt_pk_bf16_f32 v33, v28, v29
	v_add_u32_e32 v26, 0xa0, v155
	global_store_dwordx4 v[110:111], v[94:97], off offset:256 sc1
	v_cvt_pk_bf16_f32 v78, v78, v79
	v_cvt_pk_bf16_f32 v79, v80, v81
	v_mad_i64_i32 v[94:95], s[16:17], v90, s81, v[156:157]
	v_cvt_pk_bf16_f32 v80, v74, v75
	v_cvt_pk_bf16_f32 v81, v76, v77
	v_or_b32_e32 v74, 48, v155
	global_store_dwordx4 v[46:47], v[30:33], off offset:256 sc1
	v_cvt_pk_bf16_f32 v14, v14, v15
	v_cvt_pk_bf16_f32 v15, v16, v17
	v_mad_i64_i32 v[30:31], s[16:17], v26, s81, v[156:157]
	v_cvt_pk_bf16_f32 v16, v10, v11
	v_cvt_pk_bf16_f32 v17, v12, v13
	v_add_u32_e32 v10, 0xb0, v155
	v_cvt_pk_bf16_f32 v126, v126, v127
	v_cvt_pk_bf16_f32 v127, v128, v129
	v_cvt_pk_bf16_f32 v128, v122, v123
	v_cvt_pk_bf16_f32 v129, v124, v125
	v_cvt_pk_bf16_f32 v106, v118, v119
	v_cvt_pk_bf16_f32 v107, v120, v121
	v_cvt_pk_bf16_f32 v108, v114, v115
	v_cvt_pk_bf16_f32 v109, v116, v117
	v_cvt_pk_bf16_f32 v90, v102, v103
	v_cvt_pk_bf16_f32 v91, v104, v105
	v_cvt_pk_bf16_f32 v92, v98, v99
	v_cvt_pk_bf16_f32 v93, v100, v101
	global_store_dwordx4 v[94:95], v[78:81], off offset:256 sc1
	v_cvt_pk_bf16_f32 v75, v88, v89
	v_cvt_pk_bf16_f32 v76, v82, v83
	v_mad_i64_i32 v[78:79], s[16:17], v74, s81, v[156:157]
	v_cvt_pk_bf16_f32 v74, v86, v87
	v_cvt_pk_bf16_f32 v77, v84, v85
	v_cvt_pk_bf16_f32 v73, v68, v69
	v_cvt_pk_bf16_f32 v62, v62, v63
	v_cvt_pk_bf16_f32 v63, v64, v65
	v_cvt_pk_bf16_f32 v64, v58, v59
	v_cvt_pk_bf16_f32 v65, v60, v61
	v_cvt_pk_bf16_f32 v42, v54, v55
	v_cvt_pk_bf16_f32 v43, v56, v57
	v_cvt_pk_bf16_f32 v44, v50, v51
	v_cvt_pk_bf16_f32 v45, v52, v53
	v_cvt_pk_bf16_f32 v26, v38, v39
	v_cvt_pk_bf16_f32 v27, v40, v41
	v_cvt_pk_bf16_f32 v28, v34, v35
	v_cvt_pk_bf16_f32 v29, v36, v37
	global_store_dwordx4 v[30:31], v[14:17], off offset:256 sc1
	v_cvt_pk_bf16_f32 v11, v24, v25
	v_cvt_pk_bf16_f32 v12, v18, v19
	v_mad_i64_i32 v[14:15], s[16:17], v10, s81, v[156:157]
	v_cvt_pk_bf16_f32 v10, v22, v23
	v_cvt_pk_bf16_f32 v13, v20, v21
	v_cvt_pk_bf16_f32 v4, v4, v5
	v_cvt_pk_bf16_f32 v5, v6, v7
	v_cvt_pk_bf16_f32 v6, v0, v1
	v_cvt_pk_bf16_f32 v7, v2, v3
	s_and_b64 vcc, exec, s[38:39]
	s_mov_b32 s40, s72
	s_mov_b32 s42, s74
	s_mov_b64 s[70:71], s[88:89]
	s_mov_b64 s[78:79], s[66:67]
	global_store_dwordx4 v[158:159], v[126:129], off sc1
	global_store_dwordx4 v[110:111], v[106:109], off sc1
	global_store_dwordx4 v[94:95], v[90:93], off sc1
	global_store_dwordx4 v[78:79], v[74:77], off sc1
	global_store_dwordx4 v[78:79], v[70:73], off offset:256 sc1
	global_store_dwordx4 v[66:67], v[62:65], off sc1
	global_store_dwordx4 v[46:47], v[42:45], off sc1
	global_store_dwordx4 v[30:31], v[26:29], off sc1
	global_store_dwordx4 v[14:15], v[10:13], off sc1
	global_store_dwordx4 v[14:15], v[4:7], off offset:256 sc1
	s_cbranch_vccz .LBB0_643
	s_waitcnt vmcnt(0)
	s_cmpk_gt_u32 s6, 0xff
	s_cbranch_scc1 .LBB0_650
	s_barrier

; #define PG8_STAGE(bufoff, gbase, voff) do { _Pragma("unroll") for (int _i = 0; _i < 2; ++_i) \
;         __builtin_amdgcn_global_load_lds((const unsigned*)((const char*)(gbase) + (voff)[_i]), (LAS unsigned*)(lds + (bufoff) + ldsw + _i * 8192), 16, 0, 0); } while (0)
; #define PG8_LDA(dst, b, h) do { _Pragma("unroll") for (int m = 0; m < 4; ++m) _Pragma("unroll") for (int k = 0; k < 2; ++k) dst[m][k] = *(const LAS bf16x8*)(lds + PG8_SA(b, h) + aoff + m * 2048 + k * 1024); } while (0)
; #define PG8_LDB(dst, b, h) do { _Pragma("unroll") for (int n = 0; n < 2; ++n) _Pragma("unroll") for (int k = 0; k < 2; ++k) dst[n][k] = *(const LAS bf16x8*)(lds + PG8_SB(b, h) + boff + n * 2048 + k * 1024); } while (0)
; #define PG8_MMA(ai, bj, At, Bt) do { __builtin_amdgcn_s_setprio(1); _Pragma("unroll") for (int m = 0; m < 4; ++m) _Pragma("unroll") for (int n = 0; n < 2; ++n) _Pragma("unroll") for (int k = 0; k < 2; ++k) \
;         acc[ai][bj][m][n] = __builtin_amdgcn_mfma_f32_16x16x32_bf16(Bt[n][k], At[m][k], acc[ai][bj][m][n], 0, 0, 0); __builtin_amdgcn_s_setprio(0); } while (0)
; #define PG8_WAIT_L(n) asm volatile("s_waitcnt lgkmcnt(" #n ")" ::: "memory")
; #define PG8_BAR __builtin_amdgcn_s_barrier()
; #define PG8_SCHED __builtin_amdgcn_sched_barrier(0)
; template <class Epi, class Sched>
; __device__ __forceinline__ void gemm_phase(LAS unsigned char* lds, const Gemm g, const Sched& S, const Epi& E) {
;     ...
;         for (int t = 0; t < nt; t += 2) {
;             const bool last = (t == nt - 2);
;             const char* a1 = cA + (size_t)(t + 1) * kstep;
;             const char* a2 = last ? nA : cA + (size_t)(t + 2) * kstep; const char* b2 = last ? nB : cB + (size_t)(t + 2) * kstep;
;             const char* a3 = a2 + kstep; const char* b3 = b2 + kstep;
;             if (last && has_next) S.a_ready(nxt);
;             PG8_LDB(B0, 0, 0); PG8_SCHED; PG8_LDA(At, 0, 0); PG8_STAGE(PG8_SA(1, 1), a1 + hstep, voffA);
;             PG8_WAIT_L(8); PG8_BAR; PG8_WAIT_L(0); PG8_MMA(0, 0, At, B0); PG8_BAR; PG8_SCHED;
;             PG8_LDB(B1, 0, 1); PG8_STAGE(PG8_SB(0, 0), b2, voffB);
;             PG8_BAR; PG8_WAIT_L(0); PG8_MMA(0, 1, At, B1); PG8_BAR;
;             PG8_LDA(At, 0, 1); PG8_STAGE(PG8_SA(0, 0), a2, voffA);
;             PG8_BAR; PG8_WAIT_L(0); PG8_MMA(1, 0, At, B0); PG8_BAR; PG8_SCHED;
.LBB0_825:
	s_add_u32 s72, s42, 0x100
	s_addc_u32 s73, s43, 0
	s_add_i32 s19, 16, 0x10000
	v_add_u32_e32 v155, s19, v152
	ds_read_b128 v[156:159], v155
	ds_read_b128 v[160:163], v155 offset:1024
	ds_read_b128 v[164:167], v155 offset:2048
	ds_read_b128 v[168:171], v155 offset:3072
	s_cmp_eq_u32 s18, 40
	s_cselect_b32 s71, s41, s73
	s_cselect_b32 s70, s40, s72
	s_cselect_b32 s67, s1, s17
	s_cselect_b32 s66, s0, s16
	v_lshl_add_u64 v[216:217], s[42:43], 0, v[148:149]
	s_add_i32 m0, s11, 0xc000
	ds_read_b128 v[172:175], v154
	ds_read_b128 v[188:191], v154 offset:1024
	ds_read_b128 v[192:195], v154 offset:2048
	ds_read_b128 v[196:199], v154 offset:3072
	ds_read_b128 v[200:203], v154 offset:4096
	ds_read_b128 v[204:207], v154 offset:5120
	ds_read_b128 v[208:211], v154 offset:6144
	ds_read_b128 v[212:215], v154 offset:7168
	global_load_lds_dwordx4 v[216:217], off
	v_lshl_add_u64 v[216:217], s[42:43], 0, v[150:151]
	s_add_i32 m0, s11, 0xe000
	s_nop 0
	global_load_lds_dwordx4 v[216:217], off
	s_waitcnt lgkmcnt(8)
	s_barrier
	s_waitcnt lgkmcnt(0)
	s_setprio 1
	s_waitcnt lgkmcnt(0)
	v_mfma_f32_16x16x32_bf16 v[126:129], v[156:159], v[172:175], v[126:129]
	v_mfma_f32_16x16x32_bf16 v[122:125], v[164:167], v[172:175], v[122:125]
	v_mfma_f32_16x16x32_bf16 v[118:121], v[156:159], v[192:195], v[118:121]
	v_mfma_f32_16x16x32_bf16 v[114:117], v[164:167], v[192:195], v[114:117]
	v_mfma_f32_16x16x32_bf16 v[102:105], v[156:159], v[200:203], v[102:105]
	v_mfma_f32_16x16x32_bf16 v[98:101], v[164:167], v[200:203], v[98:101]
	v_mfma_f32_16x16x32_bf16 v[86:89], v[156:159], v[208:211], v[86:89]
	v_mfma_f32_16x16x32_bf16 v[82:85], v[164:167], v[208:211], v[82:85]
	v_mfma_f32_16x16x32_bf16 v[126:129], v[160:163], v[188:191], v[126:129]
	v_mfma_f32_16x16x32_bf16 v[122:125], v[168:171], v[188:191], v[122:125]
	v_mfma_f32_16x16x32_bf16 v[118:121], v[160:163], v[196:199], v[118:121]
	v_mfma_f32_16x16x32_bf16 v[114:117], v[168:171], v[196:199], v[114:117]
	v_mfma_f32_16x16x32_bf16 v[102:105], v[160:163], v[204:207], v[102:105]
	v_mfma_f32_16x16x32_bf16 v[98:101], v[168:171], v[204:207], v[98:101]
	v_mfma_f32_16x16x32_bf16 v[86:89], v[160:163], v[212:215], v[86:89]
	v_mfma_f32_16x16x32_bf16 v[82:85], v[168:171], v[212:215], v[82:85]
	s_setprio 0
	s_barrier
	s_add_i32 s22, 16, 0x14000
	s_add_i32 s19, s19, s9
	v_add_u32_e32 v155, s22, v152
	v_lshl_add_u64 v[232:233], s[66:67], 0, v[144:145]
	s_mov_b32 m0, s19
	ds_read_b128 v[216:219], v155
	ds_read_b128 v[220:223], v155 offset:1024
	ds_read_b128 v[224:227], v155 offset:2048
	ds_read_b128 v[228:231], v155 offset:3072
	global_load_lds_dwordx4 v[232:233], off
	v_lshl_add_u64 v[234:235], s[66:67], 0, v[140:141]
	s_add_i32 m0, s19, 0x2000
	s_nop 0
	global_load_lds_dwordx4 v[234:235], off
	s_barrier
	s_waitcnt lgkmcnt(0)
	s_setprio 1
	s_waitcnt lgkmcnt(0)
	v_mfma_f32_16x16x32_bf16 v[110:113], v[216:219], v[172:175], v[110:113]
	v_mfma_f32_16x16x32_bf16 v[106:109], v[224:227], v[172:175], v[106:109]
	v_mfma_f32_16x16x32_bf16 v[94:97], v[216:219], v[192:195], v[94:97]
	v_mfma_f32_16x16x32_bf16 v[90:93], v[224:227], v[192:195], v[90:93]
	v_mfma_f32_16x16x32_bf16 v[78:81], v[216:219], v[200:203], v[78:81]
	v_mfma_f32_16x16x32_bf16 v[74:77], v[224:227], v[200:203], v[74:77]
	v_mfma_f32_16x16x32_bf16 v[70:73], v[216:219], v[208:211], v[70:73]
	v_mfma_f32_16x16x32_bf16 v[66:69], v[224:227], v[208:211], v[66:69]
	v_mfma_f32_16x16x32_bf16 v[110:113], v[220:223], v[188:191], v[110:113]
	v_mfma_f32_16x16x32_bf16 v[106:109], v[228:231], v[188:191], v[106:109]
	v_mfma_f32_16x16x32_bf16 v[94:97], v[220:223], v[196:199], v[94:97]
	v_mfma_f32_16x16x32_bf16 v[90:93], v[228:231], v[196:199], v[90:93]
	v_mfma_f32_16x16x32_bf16 v[78:81], v[220:223], v[204:207], v[78:81]
	v_mfma_f32_16x16x32_bf16 v[74:77], v[228:231], v[204:207], v[74:77]
	v_mfma_f32_16x16x32_bf16 v[70:73], v[220:223], v[212:215], v[70:73]
	v_mfma_f32_16x16x32_bf16 v[66:69], v[228:231], v[212:215], v[66:69]
	s_setprio 0
	s_mov_b32 m0, s11
	v_lshl_add_u64 v[236:237], s[70:71], 0, v[146:147]
	s_barrier
	ds_read_b128 v[172:175], v154 offset:16384
	ds_read_b128 v[188:191], v154 offset:17408
	ds_read_b128 v[192:195], v154 offset:18432
	ds_read_b128 v[196:199], v154 offset:19456
	ds_read_b128 v[200:203], v154 offset:20480
	ds_read_b128 v[204:207], v154 offset:21504
	ds_read_b128 v[208:211], v154 offset:22528
	ds_read_b128 v[212:215], v154 offset:23552
	global_load_lds_dwordx4 v[236:237], off
	v_lshl_add_u64 v[238:239], s[70:71], 0, v[142:143]
	s_mov_b32 m0, s74
	s_nop 0
	global_load_lds_dwordx4 v[238:239], off
	s_barrier
	s_waitcnt lgkmcnt(0)
	s_setprio 1
	s_waitcnt lgkmcnt(0)
	v_mfma_f32_16x16x32_bf16 v[62:65], v[156:159], v[172:175], v[62:65]
	v_mfma_f32_16x16x32_bf16 v[58:61], v[164:167], v[172:175], v[58:61]
	v_mfma_f32_16x16x32_bf16 v[54:57], v[156:159], v[192:195], v[54:57]
	v_mfma_f32_16x16x32_bf16 v[50:53], v[164:167], v[192:195], v[50:53]
	v_mfma_f32_16x16x32_bf16 v[38:41], v[156:159], v[200:203], v[38:41]
	v_mfma_f32_16x16x32_bf16 v[34:37], v[164:167], v[200:203], v[34:37]
	v_mfma_f32_16x16x32_bf16 v[22:25], v[156:159], v[208:211], v[22:25]
	v_mfma_f32_16x16x32_bf16 v[18:21], v[164:167], v[208:211], v[18:21]
	v_mfma_f32_16x16x32_bf16 v[62:65], v[160:163], v[188:191], v[62:65]
	v_mfma_f32_16x16x32_bf16 v[58:61], v[168:171], v[188:191], v[58:61]
	v_mfma_f32_16x16x32_bf16 v[54:57], v[160:163], v[196:199], v[54:57]
	v_mfma_f32_16x16x32_bf16 v[50:53], v[168:171], v[196:199], v[50:53]
	v_mfma_f32_16x16x32_bf16 v[38:41], v[160:163], v[204:207], v[38:41]
	v_mfma_f32_16x16x32_bf16 v[34:37], v[168:171], v[204:207], v[34:37]
	v_mfma_f32_16x16x32_bf16 v[22:25], v[160:163], v[212:215], v[22:25]
	v_mfma_f32_16x16x32_bf16 v[18:21], v[168:171], v[212:215], v[18:21]
	s_setprio 0
	s_barrier
; #define PG8_STAGE(bufoff, gbase, voff) do { _Pragma("unroll") for (int _i = 0; _i < 2; ++_i) \
;         __builtin_amdgcn_global_load_lds((const unsigned*)((const char*)(gbase) + (voff)[_i]), (LAS unsigned*)(lds + (bufoff) + ldsw + _i * 8192), 16, 0, 0); } while (0)
; #define PG8_LDA(dst, b, h) do { _Pragma("unroll") for (int m = 0; m < 4; ++m) _Pragma("unroll") for (int k = 0; k < 2; ++k) dst[m][k] = *(const LAS bf16x8*)(lds + PG8_SA(b, h) + aoff + m * 2048 + k * 1024); } while (0)
; #define PG8_LDB(dst, b, h) do { _Pragma("unroll") for (int n = 0; n < 2; ++n) _Pragma("unroll") for (int k = 0; k < 2; ++k) dst[n][k] = *(const LAS bf16x8*)(lds + PG8_SB(b, h) + boff + n * 2048 + k * 1024); } while (0)
; #define PG8_MMA(ai, bj, At, Bt) do { __builtin_amdgcn_s_setprio(1); _Pragma("unroll") for (int m = 0; m < 4; ++m) _Pragma("unroll") for (int n = 0; n < 2; ++n) _Pragma("unroll") for (int k = 0; k < 2; ++k) \
;         acc[ai][bj][m][n] = __builtin_amdgcn_mfma_f32_16x16x32_bf16(Bt[n][k], At[m][k], acc[ai][bj][m][n], 0, 0, 0); __builtin_amdgcn_s_setprio(0); } while (0)
; #define PG8_WAIT_V(n) asm volatile("s_waitcnt vmcnt(" #n ")" ::: "memory")
; #define PG8_WAIT_L(n) asm volatile("s_waitcnt lgkmcnt(" #n ")" ::: "memory")
; #define PG8_BAR __builtin_amdgcn_s_barrier()
; #define PG8_SCHED __builtin_amdgcn_sched_barrier(0)
; template <class Epi, class Sched>
; __device__ __forceinline__ void gemm_phase(LAS unsigned char* lds, const Gemm g, const Sched& S, const Epi& E) {
;     ...
;             PG8_STAGE(PG8_SB(0, 1), b2 + hstep, voffB);
;             PG8_WAIT_V(6); PG8_BAR; PG8_MMA(1, 1, At, B1); PG8_BAR;
;             PG8_LDB(B0, 1, 0); PG8_SCHED; PG8_LDA(At, 1, 0); PG8_STAGE(PG8_SA(0, 1), a2 + hstep, voffA);
;             PG8_WAIT_L(8); PG8_BAR; PG8_WAIT_L(0); PG8_MMA(0, 0, At, B0); PG8_BAR; PG8_SCHED;
;             PG8_LDB(B1, 1, 1); PG8_STAGE(PG8_SB(1, 0), b3, voffB);
;             PG8_BAR; PG8_WAIT_L(0); PG8_MMA(0, 1, At, B1); PG8_BAR;
;             PG8_LDA(At, 1, 1); PG8_STAGE(PG8_SA(1, 0), a3, voffA);
;             PG8_BAR; PG8_WAIT_L(0); PG8_MMA(1, 0, At, B0); PG8_BAR; PG8_SCHED;
	s_add_u32 s20, s66, 0xb0000
	s_addc_u32 s21, s67, 0
	s_add_i32 s19, s22, s9
	v_lshl_add_u64 v[156:157], s[20:21], 0, v[144:145]
	s_mov_b32 m0, s19
	s_nop 0
	global_load_lds_dwordx4 v[156:157], off
	v_lshl_add_u64 v[156:157], s[20:21], 0, v[140:141]
	s_add_i32 m0, s19, 0x2000
	s_nop 0
	global_load_lds_dwordx4 v[156:157], off
	s_waitcnt vmcnt(6)
	s_barrier
	s_setprio 1
	v_mfma_f32_16x16x32_bf16 v[46:49], v[216:219], v[172:175], v[46:49]
	v_mfma_f32_16x16x32_bf16 v[42:45], v[224:227], v[172:175], v[42:45]
	v_mfma_f32_16x16x32_bf16 v[30:33], v[216:219], v[192:195], v[30:33]
	v_mfma_f32_16x16x32_bf16 v[26:29], v[224:227], v[192:195], v[26:29]
	v_mfma_f32_16x16x32_bf16 v[14:17], v[216:219], v[200:203], v[14:17]
	v_mfma_f32_16x16x32_bf16 v[10:13], v[224:227], v[200:203], v[10:13]
	v_mfma_f32_16x16x32_bf16 v[4:7], v[216:219], v[208:211], v[4:7]
	v_mfma_f32_16x16x32_bf16 v[0:3], v[224:227], v[208:211], v[0:3]
	v_mfma_f32_16x16x32_bf16 v[46:49], v[220:223], v[188:191], v[46:49]
	v_mfma_f32_16x16x32_bf16 v[42:45], v[228:231], v[188:191], v[42:45]
	v_mfma_f32_16x16x32_bf16 v[30:33], v[220:223], v[196:199], v[30:33]
	v_mfma_f32_16x16x32_bf16 v[26:29], v[228:231], v[196:199], v[26:29]
	v_mfma_f32_16x16x32_bf16 v[14:17], v[220:223], v[204:207], v[14:17]
	v_mfma_f32_16x16x32_bf16 v[10:13], v[228:231], v[204:207], v[10:13]
	v_mfma_f32_16x16x32_bf16 v[4:7], v[220:223], v[212:215], v[4:7]
	v_mfma_f32_16x16x32_bf16 v[0:3], v[228:231], v[212:215], v[0:3]
	s_setprio 0
	s_add_i32 s19, 16, 0x18000
	v_add_u32_e32 v155, s19, v152
	s_barrier
	ds_read_b128 v[156:159], v155
	ds_read_b128 v[160:163], v155 offset:1024
	ds_read_b128 v[164:167], v155 offset:2048
	ds_read_b128 v[168:171], v155 offset:3072
	s_add_u32 s20, s70, 0xb0000
	s_addc_u32 s21, s71, 0
	s_mov_b32 m0, s12
	v_lshl_add_u64 v[216:217], s[20:21], 0, v[146:147]
	ds_read_b128 v[172:175], v154 offset:32768
	ds_read_b128 v[188:191], v154 offset:33792
	ds_read_b128 v[192:195], v154 offset:34816
	ds_read_b128 v[196:199], v154 offset:35840
	ds_read_b128 v[200:203], v154 offset:36864
	ds_read_b128 v[204:207], v154 offset:37888
	ds_read_b128 v[208:211], v154 offset:38912
	ds_read_b128 v[212:215], v154 offset:39936
	global_load_lds_dwordx4 v[216:217], off
	v_lshl_add_u64 v[216:217], s[20:21], 0, v[142:143]
	s_mov_b32 m0, s13
	s_nop 0
	global_load_lds_dwordx4 v[216:217], off
	s_waitcnt lgkmcnt(8)
	s_barrier
	s_waitcnt lgkmcnt(0)
	s_setprio 1
	s_waitcnt lgkmcnt(0)
	v_mfma_f32_16x16x32_bf16 v[126:129], v[156:159], v[172:175], v[126:129]
	v_mfma_f32_16x16x32_bf16 v[122:125], v[164:167], v[172:175], v[122:125]
	v_mfma_f32_16x16x32_bf16 v[118:121], v[156:159], v[192:195], v[118:121]
	v_mfma_f32_16x16x32_bf16 v[114:117], v[164:167], v[192:195], v[114:117]
	v_mfma_f32_16x16x32_bf16 v[102:105], v[156:159], v[200:203], v[102:105]
	v_mfma_f32_16x16x32_bf16 v[98:101], v[164:167], v[200:203], v[98:101]
	v_mfma_f32_16x16x32_bf16 v[86:89], v[156:159], v[208:211], v[86:89]
	v_mfma_f32_16x16x32_bf16 v[82:85], v[164:167], v[208:211], v[82:85]
	v_mfma_f32_16x16x32_bf16 v[126:129], v[160:163], v[188:191], v[126:129]
	v_mfma_f32_16x16x32_bf16 v[122:125], v[168:171], v[188:191], v[122:125]
	v_mfma_f32_16x16x32_bf16 v[118:121], v[160:163], v[196:199], v[118:121]
	v_mfma_f32_16x16x32_bf16 v[114:117], v[168:171], v[196:199], v[114:117]
	v_mfma_f32_16x16x32_bf16 v[102:105], v[160:163], v[204:207], v[102:105]
	v_mfma_f32_16x16x32_bf16 v[98:101], v[168:171], v[204:207], v[98:101]
	v_mfma_f32_16x16x32_bf16 v[86:89], v[160:163], v[212:215], v[86:89]
	v_mfma_f32_16x16x32_bf16 v[82:85], v[168:171], v[212:215], v[82:85]
	s_setprio 0
	s_barrier
	s_add_i32 s22, 16, 0x1c000
	s_add_i32 s19, s19, s9
	v_add_u32_e32 v155, s22, v152
	v_lshl_add_u64 v[232:233], v[232:233], 0, s[94:95]
	s_mov_b32 m0, s19
	ds_read_b128 v[216:219], v155
	ds_read_b128 v[220:223], v155 offset:1024
	ds_read_b128 v[224:227], v155 offset:2048
	ds_read_b128 v[228:231], v155 offset:3072
	global_load_lds_dwordx4 v[232:233], off
	v_lshl_add_u64 v[232:233], v[234:235], 0, s[94:95]
	s_add_i32 m0, s19, 0x2000
	s_nop 0
	global_load_lds_dwordx4 v[232:233], off
	s_barrier
	s_waitcnt lgkmcnt(0)
	s_setprio 1
	s_waitcnt lgkmcnt(0)
	v_mfma_f32_16x16x32_bf16 v[110:113], v[216:219], v[172:175], v[110:113]
	v_mfma_f32_16x16x32_bf16 v[106:109], v[224:227], v[172:175], v[106:109]
	v_mfma_f32_16x16x32_bf16 v[94:97], v[216:219], v[192:195], v[94:97]
	v_mfma_f32_16x16x32_bf16 v[90:93], v[224:227], v[192:195], v[90:93]
	v_mfma_f32_16x16x32_bf16 v[78:81], v[216:219], v[200:203], v[78:81]
	v_mfma_f32_16x16x32_bf16 v[74:77], v[224:227], v[200:203], v[74:77]
	v_mfma_f32_16x16x32_bf16 v[70:73], v[216:219], v[208:211], v[70:73]
	v_mfma_f32_16x16x32_bf16 v[66:69], v[224:227], v[208:211], v[66:69]
	v_mfma_f32_16x16x32_bf16 v[110:113], v[220:223], v[188:191], v[110:113]
	v_mfma_f32_16x16x32_bf16 v[106:109], v[228:231], v[188:191], v[106:109]
	v_mfma_f32_16x16x32_bf16 v[94:97], v[220:223], v[196:199], v[94:97]
	v_mfma_f32_16x16x32_bf16 v[90:93], v[228:231], v[196:199], v[90:93]
	v_mfma_f32_16x16x32_bf16 v[78:81], v[220:223], v[204:207], v[78:81]
	v_mfma_f32_16x16x32_bf16 v[74:77], v[228:231], v[204:207], v[74:77]
	v_mfma_f32_16x16x32_bf16 v[70:73], v[220:223], v[212:215], v[70:73]
	v_mfma_f32_16x16x32_bf16 v[66:69], v[228:231], v[212:215], v[66:69]
	s_setprio 0
	s_mov_b32 m0, s14
	v_lshl_add_u64 v[232:233], v[236:237], 0, s[94:95]
	s_barrier
	ds_read_b128 v[172:175], v154 offset:49152
	ds_read_b128 v[188:191], v154 offset:50176
	ds_read_b128 v[192:195], v154 offset:51200
	ds_read_b128 v[196:199], v154 offset:52224
	ds_read_b128 v[200:203], v154 offset:53248
	ds_read_b128 v[204:207], v154 offset:54272
	ds_read_b128 v[208:211], v154 offset:55296
	ds_read_b128 v[212:215], v154 offset:56320
	global_load_lds_dwordx4 v[232:233], off
	v_lshl_add_u64 v[232:233], v[238:239], 0, s[94:95]
	s_mov_b32 m0, s15
	s_nop 0
	global_load_lds_dwordx4 v[232:233], off
	s_barrier
; #define PG8_STAGE(bufoff, gbase, voff) do { _Pragma("unroll") for (int _i = 0; _i < 2; ++_i) \
;         __builtin_amdgcn_global_load_lds((const unsigned*)((const char*)(gbase) + (voff)[_i]), (LAS unsigned*)(lds + (bufoff) + ldsw + _i * 8192), 16, 0, 0); } while (0)
; #define PG8_MMA(ai, bj, At, Bt) do { __builtin_amdgcn_s_setprio(1); _Pragma("unroll") for (int m = 0; m < 4; ++m) _Pragma("unroll") for (int n = 0; n < 2; ++n) _Pragma("unroll") for (int k = 0; k < 2; ++k) \
;         acc[ai][bj][m][n] = __builtin_amdgcn_mfma_f32_16x16x32_bf16(Bt[n][k], At[m][k], acc[ai][bj][m][n], 0, 0, 0); __builtin_amdgcn_s_setprio(0); } while (0)
; #define PG8_WAIT_V(n) asm volatile("s_waitcnt vmcnt(" #n ")" ::: "memory")
; #define PG8_WAIT_L(n) asm volatile("s_waitcnt lgkmcnt(" #n ")" ::: "memory")
; #define PG8_BAR __builtin_amdgcn_s_barrier()
; #define PG8_SCHED __builtin_amdgcn_sched_barrier(0)
; template <class Epi, class Sched>
; __device__ __forceinline__ void gemm_phase(LAS unsigned char* lds, const Gemm g, const Sched& S, const Epi& E) {
;     ...
;             PG8_BAR; PG8_WAIT_L(0); PG8_MMA(1, 0, At, B0); PG8_BAR; PG8_SCHED;
;             PG8_STAGE(PG8_SB(1, 1), b3 + hstep, voffB);
;             PG8_WAIT_V(6); PG8_BAR; PG8_MMA(1, 1, At, B1); PG8_BAR;
;         }
	s_waitcnt lgkmcnt(0)
	s_setprio 1
	s_waitcnt lgkmcnt(0)
	v_mfma_f32_16x16x32_bf16 v[62:65], v[156:159], v[172:175], v[62:65]
	v_mfma_f32_16x16x32_bf16 v[58:61], v[164:167], v[172:175], v[58:61]
	v_mfma_f32_16x16x32_bf16 v[54:57], v[156:159], v[192:195], v[54:57]
	v_mfma_f32_16x16x32_bf16 v[50:53], v[164:167], v[192:195], v[50:53]
	v_mfma_f32_16x16x32_bf16 v[38:41], v[156:159], v[200:203], v[38:41]
	v_mfma_f32_16x16x32_bf16 v[34:37], v[164:167], v[200:203], v[34:37]
	v_mfma_f32_16x16x32_bf16 v[22:25], v[156:159], v[208:211], v[22:25]
	v_mfma_f32_16x16x32_bf16 v[18:21], v[164:167], v[208:211], v[18:21]
	v_mfma_f32_16x16x32_bf16 v[62:65], v[160:163], v[188:191], v[62:65]
	v_mfma_f32_16x16x32_bf16 v[58:61], v[168:171], v[188:191], v[58:61]
	v_mfma_f32_16x16x32_bf16 v[54:57], v[160:163], v[196:199], v[54:57]
	v_mfma_f32_16x16x32_bf16 v[50:53], v[168:171], v[196:199], v[50:53]
	v_mfma_f32_16x16x32_bf16 v[38:41], v[160:163], v[204:207], v[38:41]
	v_mfma_f32_16x16x32_bf16 v[34:37], v[168:171], v[204:207], v[34:37]
	v_mfma_f32_16x16x32_bf16 v[22:25], v[160:163], v[212:215], v[22:25]
	v_mfma_f32_16x16x32_bf16 v[18:21], v[168:171], v[212:215], v[18:21]
	s_setprio 0
	s_barrier
	s_add_u32 s20, s66, 0xb0080
	s_addc_u32 s21, s67, 0
	s_add_i32 s19, s22, s9
	v_lshl_add_u64 v[156:157], s[20:21], 0, v[144:145]
	s_mov_b32 m0, s19
	s_nop 0
	global_load_lds_dwordx4 v[156:157], off
	v_lshl_add_u64 v[156:157], s[20:21], 0, v[140:141]
	s_add_i32 m0, s19, 0x2000
	s_nop 0
	global_load_lds_dwordx4 v[156:157], off
	s_waitcnt vmcnt(6)
	s_barrier
	s_setprio 1
	v_mfma_f32_16x16x32_bf16 v[46:49], v[216:219], v[172:175], v[46:49]
	v_mfma_f32_16x16x32_bf16 v[42:45], v[224:227], v[172:175], v[42:45]
	v_mfma_f32_16x16x32_bf16 v[30:33], v[216:219], v[192:195], v[30:33]
	v_mfma_f32_16x16x32_bf16 v[26:29], v[224:227], v[192:195], v[26:29]
	v_mfma_f32_16x16x32_bf16 v[14:17], v[216:219], v[200:203], v[14:17]
	v_mfma_f32_16x16x32_bf16 v[10:13], v[224:227], v[200:203], v[10:13]
	v_mfma_f32_16x16x32_bf16 v[4:7], v[216:219], v[208:211], v[4:7]
	v_mfma_f32_16x16x32_bf16 v[0:3], v[224:227], v[208:211], v[0:3]
	v_mfma_f32_16x16x32_bf16 v[46:49], v[220:223], v[188:191], v[46:49]
	v_mfma_f32_16x16x32_bf16 v[42:45], v[228:231], v[188:191], v[42:45]
	v_mfma_f32_16x16x32_bf16 v[30:33], v[220:223], v[196:199], v[30:33]
	v_mfma_f32_16x16x32_bf16 v[26:29], v[228:231], v[196:199], v[26:29]
	v_mfma_f32_16x16x32_bf16 v[14:17], v[220:223], v[204:207], v[14:17]
	v_mfma_f32_16x16x32_bf16 v[10:13], v[228:231], v[204:207], v[10:13]
	v_mfma_f32_16x16x32_bf16 v[4:7], v[220:223], v[212:215], v[4:7]
	v_mfma_f32_16x16x32_bf16 v[0:3], v[228:231], v[212:215], v[0:3]
	s_setprio 0
	s_add_i32 s18, s18, 2
	s_add_u32 s16, s16, 0x100
	s_addc_u32 s17, s17, 0
	s_cmp_gt_u32 s18, 41
	s_mov_b64 s[42:43], s[72:73]
	s_barrier
	s_cbranch_scc0 .LBB0_825
; __device__ __forceinline__ unsigned pk_bf16(float a, float b) { f32x2 v = {a, b}; bf2_t r = __builtin_convertvector(v, bf2_t); return __builtin_bit_cast(unsigned, r); }
; #define PG8_WAIT_V(n) asm volatile("s_waitcnt vmcnt(" #n ")" ::: "memory")
; #define PG8_BAR __builtin_amdgcn_s_barrier()
;     __device__ __forceinline__ void operator()(const f32x4 (&acc)[2][2][4][2], const Unit& u, int wr, int wc, int fr, int fq) const {
;         const int row0 = u.pm * BM + wr * 64 + fr; int colt = u.pn * BM; bf16_t* base = O;
;         if (split_cols) { const int t = colt / split_cols; base += (size_t)t * split_stride; colt -= t * split_cols; }
;         const int col0 = colt + wc * 32 + 8 * fq;
; #pragma unroll
;         for (int ai = 0; ai < 2; ++ai)
; #pragma unroll
;             for (int m = 0; m < 4; ++m) { const int row = row0 + ai * HALF + m * 16;
;                 bf16_t* rowp = slot_stride ? base + (size_t)(colt >> 7) * slot_stride + (size_t)row * 128 + wc * 32 + 8 * fq : base + (size_t)row * ldc + col0;
; #pragma unroll
;                 for (int bj = 0; bj < 2; ++bj) { const f32x4 v0 = acc[ai][bj][m][0], v1 = acc[ai][bj][m][1];
;                     u32x4 w; w.x = pk_bf16(v0[0], v0[1]); w.y = pk_bf16(v0[2], v0[3]); w.z = pk_bf16(v1[0], v1[1]); w.w = pk_bf16(v1[2], v1[3]);
;                     *(u32x4*)(rowp + (slot_stride ? (size_t)bj * slot_stride : (size_t)bj * HALF)) = w; } }
; template <class Epi, class Sched>
; __device__ __forceinline__ void gemm_phase(LAS unsigned char* lds, const Gemm g, const Sched& S, const Epi& E) {
;     ...
;         E(acc, cur, wr, wc, fr, fq); S.done(cur);
;         if (!has_next) break;
; #pragma unroll
;         for (int a = 0; a < 2; ++a)
; #pragma unroll
;             for (int b = 0; b < 2; ++b)
; #pragma unroll
;                 for (int m = 0; m < 4; ++m)
; #pragma unroll
;                     for (int n = 0; n < 2; ++n) acc[a][b][m][n] = (f32x4){0.f, 0.f, 0.f, 0.f};
;         cur = nxt; cA = nA; cB = nB; ++ui;
;     }
;     PG8_WAIT_V(0);
;     if (wr == 0) PG8_BAR;
;     PG8_BAR;
	v_lshl_add_u32 v156, s78, 8, v9
	v_lshl_or_b32 v158, s75, 8, v153
	v_readlane_b32 s16, v244, 38
	v_ashrrev_i32_e32 v159, 31, v158
	v_readlane_b32 s17, v244, 39
	v_ashrrev_i32_e32 v157, 31, v156
	v_lshlrev_b64 v[160:161], 11, v[156:157]
	v_lshl_add_u64 v[158:159], v[158:159], 1, s[16:17]
	v_lshl_add_u64 v[160:161], v[158:159], 0, v[160:161]
	s_mov_b64 s[16:17], 0x40000
	v_cvt_pk_bf16_f32 v70, v70, v71
	v_cvt_pk_bf16_f32 v71, v72, v73
	v_cvt_pk_bf16_f32 v72, v66, v67
	v_lshl_add_u64 v[66:67], v[160:161], 0, s[16:17]
	s_mov_b32 s16, 0x40000
	v_cvt_pk_bf16_f32 v62, v62, v63
	v_cvt_pk_bf16_f32 v63, v64, v65
	v_cvt_pk_bf16_f32 v64, v58, v59
	v_add_co_u32_e32 v58, vcc, s16, v160
	v_cvt_pk_bf16_f32 v46, v46, v47
	v_cvt_pk_bf16_f32 v47, v48, v49
	v_cvt_pk_bf16_f32 v48, v42, v43
	v_cvt_pk_bf16_f32 v49, v44, v45
	s_mov_b64 s[16:17], 0x48000
	v_addc_co_u32_e32 v59, vcc, 0, v161, vcc
	global_store_dwordx4 v[66:67], v[46:49], off offset:256 sc1
	v_cvt_pk_bf16_f32 v30, v30, v31
	v_cvt_pk_bf16_f32 v31, v32, v33
	v_lshl_add_u64 v[46:47], v[160:161], 0, s[16:17]
	s_mov_b32 s16, 0x48000
	v_add_co_u32_e32 v48, vcc, s16, v160
	v_cvt_pk_bf16_f32 v32, v26, v27
	v_cvt_pk_bf16_f32 v33, v28, v29
	s_mov_b64 s[16:17], 0x50000
	v_cvt_pk_bf16_f32 v110, v110, v111
	v_cvt_pk_bf16_f32 v111, v112, v113
	v_cvt_pk_bf16_f32 v112, v106, v107
	v_or_b32_e32 v106, 16, v156
	v_addc_co_u32_e32 v49, vcc, 0, v161, vcc
	global_store_dwordx4 v[46:47], v[30:33], off offset:256 sc1
	v_ashrrev_i32_e32 v107, 31, v106
	v_cvt_pk_bf16_f32 v94, v94, v95
	v_lshl_add_u64 v[30:31], v[160:161], 0, s[16:17]
	s_mov_b32 s16, 0x50000
	v_cvt_pk_bf16_f32 v95, v96, v97
	v_cvt_pk_bf16_f32 v96, v90, v91
	v_or_b32_e32 v90, 32, v156
	v_add_co_u32_e32 v32, vcc, s16, v160
	v_cvt_pk_bf16_f32 v14, v14, v15
	v_cvt_pk_bf16_f32 v15, v16, v17
	v_cvt_pk_bf16_f32 v16, v10, v11
	v_cvt_pk_bf16_f32 v17, v12, v13
	s_mov_b64 s[16:17], 0x58000
	v_cvt_pk_bf16_f32 v113, v108, v109
	v_lshlrev_b64 v[106:107], 11, v[106:107]
	v_ashrrev_i32_e32 v91, 31, v90
	v_cvt_pk_bf16_f32 v78, v78, v79
	v_cvt_pk_bf16_f32 v79, v80, v81
	v_cvt_pk_bf16_f32 v80, v74, v75
	v_or_b32_e32 v74, 48, v156
	v_addc_co_u32_e32 v33, vcc, 0, v161, vcc
	global_store_dwordx4 v[30:31], v[14:17], off offset:256 sc1
	global_store_dwordx4 v[160:161], v[110:113], off offset:256 sc1
	v_cvt_pk_bf16_f32 v97, v92, v93
	v_lshl_add_u64 v[14:15], v[160:161], 0, s[16:17]
	s_mov_b32 s16, 0x58000
	v_lshl_add_u64 v[110:111], v[158:159], 0, v[106:107]
	v_lshlrev_b64 v[90:91], 11, v[90:91]
	v_ashrrev_i32_e32 v75, 31, v74
	v_add_co_u32_e32 v16, vcc, s16, v160
	global_store_dwordx4 v[110:111], v[94:97], off offset:256 sc1
	v_cvt_pk_bf16_f32 v81, v76, v77
	v_lshlrev_b64 v[74:75], 11, v[74:75]
	v_lshl_add_u64 v[94:95], v[158:159], 0, v[90:91]
	v_addc_co_u32_e32 v17, vcc, 0, v161, vcc
	v_readlane_b32 s70, v244, 55
	v_cvt_pk_bf16_f32 v126, v126, v127
	v_cvt_pk_bf16_f32 v127, v128, v129
	v_cvt_pk_bf16_f32 v128, v122, v123
	v_cvt_pk_bf16_f32 v129, v124, v125
	v_cvt_pk_bf16_f32 v106, v118, v119
	v_cvt_pk_bf16_f32 v107, v120, v121
	v_cvt_pk_bf16_f32 v108, v114, v115
	v_cvt_pk_bf16_f32 v109, v116, v117
	v_cvt_pk_bf16_f32 v90, v102, v103
	v_cvt_pk_bf16_f32 v91, v104, v105
	v_cvt_pk_bf16_f32 v92, v98, v99
	v_cvt_pk_bf16_f32 v93, v100, v101
	global_store_dwordx4 v[94:95], v[78:81], off offset:256 sc1
	v_cvt_pk_bf16_f32 v76, v82, v83
	v_cvt_pk_bf16_f32 v77, v84, v85
	v_lshl_add_u64 v[78:79], v[158:159], 0, v[74:75]
	v_cvt_pk_bf16_f32 v74, v86, v87
	v_cvt_pk_bf16_f32 v75, v88, v89
	v_cvt_pk_bf16_f32 v73, v68, v69
	v_cvt_pk_bf16_f32 v65, v60, v61
	v_cvt_pk_bf16_f32 v42, v54, v55
	v_cvt_pk_bf16_f32 v43, v56, v57
	v_cvt_pk_bf16_f32 v44, v50, v51
	v_cvt_pk_bf16_f32 v45, v52, v53
	v_cvt_pk_bf16_f32 v26, v38, v39
	v_cvt_pk_bf16_f32 v27, v40, v41
	v_cvt_pk_bf16_f32 v28, v34, v35
	v_cvt_pk_bf16_f32 v29, v36, v37
	v_cvt_pk_bf16_f32 v10, v22, v23
	v_cvt_pk_bf16_f32 v11, v24, v25
	v_cvt_pk_bf16_f32 v12, v18, v19
	v_cvt_pk_bf16_f32 v13, v20, v21
	v_cvt_pk_bf16_f32 v4, v4, v5
	v_cvt_pk_bf16_f32 v5, v6, v7
	v_cvt_pk_bf16_f32 v6, v0, v1
	v_cvt_pk_bf16_f32 v7, v2, v3
	s_and_b64 vcc, exec, s[38:39]
	s_mov_b32 s75, s85
	s_mov_b32 s78, s88
	s_mov_b64 s[72:73], s[0:1]
	s_mov_b64 s[42:43], s[40:41]
	v_readlane_b32 s71, v244, 56
	global_store_dwordx4 v[160:161], v[126:129], off sc1
	global_store_dwordx4 v[110:111], v[106:109], off sc1
	global_store_dwordx4 v[94:95], v[90:93], off sc1
	global_store_dwordx4 v[78:79], v[74:77], off sc1
	global_store_dwordx4 v[78:79], v[70:73], off offset:256 sc1
	global_store_dwordx4 v[58:59], v[62:65], off sc1
	global_store_dwordx4 v[48:49], v[42:45], off sc1
	global_store_dwordx4 v[32:33], v[26:29], off sc1
	global_store_dwordx4 v[16:17], v[10:13], off sc1
	global_store_dwordx4 v[14:15], v[4:7], off offset:256 sc1
	s_cbranch_vccz .LBB0_818
	s_waitcnt vmcnt(0)
	v_readlane_b32 s16, v244, 51
	s_cmpk_gt_u32 s6, 0xff
	v_readlane_b32 s17, v244, 52
	s_cbranch_scc1 .LBB0_829
	s_barrier
